# v29
# baseline (speedup 1.0000x reference)
.LBB0_499:
	s_andn2_saveexec_b64 s[12:13], s[28:29]
	s_cbranch_execz .LBB0_534
	s_cmp_eq_u32 s26, -16
	s_cbranch_scc1 .LBB0_534
	s_bitcmp1_b32 s34, 0
	s_cselect_b32 s28, 0x5180, 0
	v_add_u32_e32 v50, s28, v72
	v_lshl_add_u32 v59, v74, 2, v50
	s_waitcnt lgkmcnt(0)
	ds_read_b128 v[34:37], v59
	ds_read_b128 v[38:41], v59 offset:32
	ds_read_b128 v[42:45], v59 offset:768
	ds_read_b128 v[162:165], v59 offset:800
	ds_read_b128 v[166:169], v59 offset:64
	ds_read_b128 v[170:173], v59 offset:96
	ds_read_b128 v[174:177], v59 offset:832
	ds_read_b128 v[178:181], v59 offset:864
	ds_read_b128 v[182:185], v59 offset:128
	ds_read_b128 v[186:189], v59 offset:160
	ds_read_b128 v[190:193], v59 offset:192
	ds_read_b128 v[194:197], v59 offset:224
	s_waitcnt lgkmcnt(11)
	v_mul_f32_e32 v36, v2, v36
	v_mul_f32_e32 v37, v3, v37
	v_mul_f32_e32 v34, v0, v34
	v_mul_f32_e32 v35, v1, v35
	s_waitcnt lgkmcnt(3)
	v_mul_f32_e32 v46, v18, v184
	v_mul_f32_e32 v47, v19, v185
	v_mul_f32_e32 v182, v16, v182
	v_mul_f32_e32 v183, v17, v183
	v_fma_f32 v36, v6, v40, v36
	v_fma_f32 v37, v7, v41, v37
	v_fma_f32 v34, v4, v38, v34
	v_fma_f32 v35, v5, v39, v35
	s_waitcnt lgkmcnt(2)
	v_fma_f32 v38, v22, v188, v46
	v_fma_f32 v39, v23, v189, v47
	v_lshl_add_u32 v61, v102, 2, v50
	v_fma_f32 v40, v20, v186, v182
	v_fma_f32 v41, v21, v187, v183
	v_fma_f32 v36, v10, v168, v36
	v_fma_f32 v37, v11, v169, v37
	v_fma_f32 v34, v8, v166, v34
	v_fma_f32 v35, v9, v167, v35
	s_waitcnt lgkmcnt(1)
	v_fma_f32 v38, v26, v192, v38
	v_fma_f32 v39, v27, v193, v39
	ds_read2_b32 v[198:199], v61 offset0:64 offset1:96
	v_fma_f32 v40, v24, v190, v40
	v_fma_f32 v41, v25, v191, v41
	v_fma_f32 v36, v14, v172, v36
	v_fma_f32 v37, v15, v173, v37
	v_fma_f32 v34, v12, v170, v34
	v_fma_f32 v35, v13, v171, v35
	s_waitcnt lgkmcnt(1)
	v_fma_f32 v38, v30, v196, v38
	v_fma_f32 v39, v31, v197, v39
	v_fma_f32 v40, v28, v194, v40
	v_fma_f32 v41, v29, v195, v41
	v_add_f32_e32 v32, v34, v35
	v_add_f32_e32 v34, v36, v37
	v_add_f32_e32 v35, v38, v39
	v_mul_f32_e32 v36, v2, v44
	v_mul_f32_e32 v37, v3, v45
	v_mul_f32_e32 v38, v0, v42
	v_mul_f32_e32 v39, v1, v43
	v_lshl_add_u32 v158, v75, 2, v50
	v_add_f32_e32 v32, v32, v34
	v_add_f32_e32 v34, v40, v41
	v_fma_f32 v36, v6, v164, v36
	v_fma_f32 v37, v7, v165, v37
	v_fma_f32 v38, v4, v162, v38
	v_fma_f32 v39, v5, v163, v39
	ds_read_b32 v33, v158 offset:1024
	ds_read_b64 v[170:171], v50 offset:20736
	v_add_f32_e32 v34, v34, v35
	v_fma_f32 v36, v10, v176, v36
	v_fma_f32 v37, v11, v177, v37
	v_fma_f32 v38, v8, v174, v38
	v_fma_f32 v39, v9, v175, v39
	v_add_f32_e32 v32, v32, v34
	v_fma_f32 v166, v14, v180, v36
	v_fma_f32 v167, v15, v181, v37
	v_fma_f32 v168, v12, v178, v38
	v_fma_f32 v169, v13, v179, v39
	ds_read_b128 v[36:39], v59 offset:896
	ds_read_b128 v[40:43], v59 offset:928
	ds_read_b128 v[44:47], v59 offset:960
	ds_read_b128 v[162:165], v59 offset:992
	v_mov_b32_e32 v34, v32
	s_nop 1
	v_permlane32_swap_b32_e32 v32, v34
	s_waitcnt lgkmcnt(3)
	v_mul_f32_e32 v38, v18, v38
	v_mul_f32_e32 v39, v19, v39
	v_mul_f32_e32 v36, v16, v36
	v_mul_f32_e32 v37, v17, v37
	v_add_f32_e32 v35, v32, v34
	s_waitcnt lgkmcnt(2)
	v_fma_f32 v38, v22, v42, v38
	v_fma_f32 v39, v23, v43, v39
	v_fma_f32 v36, v20, v40, v36
	v_fma_f32 v37, v21, v41, v37
	v_cndmask_b32_e64 v32, v33, v35, s[6:7]
	s_waitcnt lgkmcnt(1)
	v_fma_f32 v38, v26, v46, v38
	v_fma_f32 v39, v27, v47, v39
	v_fma_f32 v36, v24, v44, v36
	v_fma_f32 v37, v25, v45, v37
	v_mfma_f32_32x32x2_f32 v[0:15], v198, v32, v[0:15]
	s_waitcnt lgkmcnt(0)
	v_fma_f32 v38, v30, v164, v38
	v_fma_f32 v39, v31, v165, v39
	v_fma_f32 v36, v28, v162, v36
	v_fma_f32 v37, v29, v163, v37
	v_add_f32_e32 v34, v166, v167
	v_mfma_f32_32x32x2_f32 v[16:31], v199, v32, v[16:31]
	v_add_f32_e32 v32, v168, v169
	v_add_f32_e32 v32, v32, v34
	v_add_f32_e32 v34, v36, v37
	v_add_f32_e32 v36, v38, v39
	v_add_f32_e32 v34, v34, v36
	v_add_f32_e32 v32, v32, v34
	v_mov_b32_e32 v34, v32
	s_nop 1
	v_permlane32_swap_b32_e32 v32, v34
	s_and_saveexec_b64 s[28:29], s[6:7]
	s_cbranch_execz .LBB0_503
	s_add_i32 s39, s30, 39
	s_and_b64 s[34:35], s[8:9], exec
	s_cselect_b32 s34, s26, s39
	s_ashr_i32 s35, s34, 31
	s_waitcnt lgkmcnt(0)
	v_mul_f32_e32 v35, v35, v170
	v_mul_f32_e32 v33, v33, v171
	v_pk_add_f32 v[32:33], v[32:33], v[34:35]
	s_nop 0
	v_add_f32_e32 v34, v32, v33
	v_lshl_add_u64 v[32:33], v[66:67], 0, s[34:35]
	v_lshlrev_b64 v[32:33], 11, v[32:33]
	v_lshl_add_u64 v[32:33], v[68:69], 0, v[32:33]
	global_store_dword v[32:33], v34, off
.LBB0_503:
	s_or_b64 exec, exec, s[28:29]
	ds_read_b128 v[32:35], v59 offset:1280
	ds_read_b128 v[36:39], v59 offset:1312
	ds_read_b128 v[162:165], v59 offset:2048
	ds_read_b128 v[166:169], v59 offset:2080
	ds_read_b128 v[40:43], v59 offset:1344
	ds_read_b128 v[44:47], v59 offset:1376
	ds_read_b128 v[170:173], v59 offset:2112
	ds_read_b128 v[174:177], v59 offset:2144
	ds_read_b128 v[178:181], v59 offset:1408
	ds_read_b128 v[182:185], v59 offset:1440
	ds_read_b128 v[186:189], v59 offset:2176
	ds_read_b128 v[190:193], v59 offset:2208
	ds_read_b128 v[194:197], v59 offset:1472
	ds_read_b128 v[198:201], v59 offset:1504
	ds_read_b128 v[202:205], v59 offset:2240
	ds_read_b128 v[206:209], v59 offset:2272
	s_waitcnt lgkmcnt(14)
	v_mul_f32_e32 v34, v2, v34
	v_mul_f32_e32 v35, v3, v35
	v_mul_f32_e32 v32, v0, v32
	v_mul_f32_e32 v33, v1, v33
	s_waitcnt lgkmcnt(7)
	v_mul_f32_e32 v180, v18, v180
	v_mul_f32_e32 v181, v19, v181
	v_mul_f32_e32 v178, v16, v178
	v_mul_f32_e32 v179, v17, v179
	v_fma_f32 v34, v6, v38, v34
	v_fma_f32 v35, v7, v39, v35
	v_fma_f32 v32, v4, v36, v32
	v_fma_f32 v33, v5, v37, v33
	s_waitcnt lgkmcnt(6)
	v_fma_f32 v36, v22, v184, v180
	v_fma_f32 v37, v23, v185, v181
	v_fma_f32 v38, v20, v182, v178
	v_fma_f32 v39, v21, v183, v179
	v_fma_f32 v32, v8, v40, v32
	v_fma_f32 v33, v9, v41, v33
	v_fma_f32 v34, v10, v42, v34
	v_fma_f32 v35, v11, v43, v35
	s_waitcnt lgkmcnt(3)
	v_fma_f32 v38, v24, v194, v38
	v_fma_f32 v39, v25, v195, v39
	v_fma_f32 v36, v26, v196, v36
	v_fma_f32 v37, v27, v197, v37
	v_fma_f32 v34, v14, v46, v34
	v_fma_f32 v35, v15, v47, v35
	v_fma_f32 v32, v12, v44, v32
	v_fma_f32 v33, v13, v45, v33
	s_waitcnt lgkmcnt(2)
	v_fma_f32 v36, v30, v200, v36
	v_fma_f32 v37, v31, v201, v37
	v_fma_f32 v38, v28, v198, v38
	v_fma_f32 v39, v29, v199, v39
	v_add_f32_e32 v32, v32, v33
	v_add_f32_e32 v33, v34, v35
	v_add_u32_e32 v159, 0x400, v61
	v_add_f32_e32 v32, v32, v33
	v_add_f32_e32 v33, v38, v39
	v_add_f32_e32 v34, v36, v37
	ds_read2_b32 v[210:211], v159 offset0:128 offset1:160
	ds_read_b32 v159, v158 offset:2304
	ds_read_b64 v[194:195], v50 offset:20744
	v_add_f32_e32 v33, v33, v34
	v_add_f32_e32 v32, v32, v33
	v_mov_b32_e32 v33, v32
	s_nop 1
	v_permlane32_swap_b32_e32 v32, v33
	v_add_f32_e32 v161, v32, v33
	s_waitcnt lgkmcnt(0)
	v_cndmask_b32_e64 v178, v159, v161, s[6:7]
	v_mul_f32_e32 v164, v2, v164
	v_mul_f32_e32 v165, v3, v165
	v_mul_f32_e32 v162, v0, v162
	v_mul_f32_e32 v163, v1, v163
	v_mfma_f32_32x32x2_f32 v[32:47], v211, v178, v[16:31]
	v_fma_f32 v18, v18, v188, 0
	v_fma_f32 v19, v19, v189, 0
	v_fma_f32 v16, v16, v186, 0
	v_fma_f32 v17, v17, v187, 0
	v_fma_f32 v164, v6, v168, v164
	v_fma_f32 v165, v7, v169, v165
	v_fma_f32 v162, v4, v166, v162
	v_fma_f32 v163, v5, v167, v163
	v_fma_f32 v18, v22, v192, v18
	v_fma_f32 v19, v23, v193, v19
	v_fma_f32 v16, v20, v190, v16
	v_fma_f32 v17, v21, v191, v17
	v_fma_f32 v20, v8, v170, v162
	v_fma_f32 v21, v9, v171, v163
	v_fma_f32 v22, v10, v172, v164
	v_fma_f32 v23, v11, v173, v165
	v_fma_f32 v20, v12, v174, v20
	v_fma_f32 v21, v13, v175, v21
	v_fma_f32 v22, v14, v176, v22
	v_fma_f32 v23, v15, v177, v23
	v_fma_f32 v16, v24, v202, v16
	v_fma_f32 v17, v25, v203, v17
	v_fma_f32 v18, v26, v204, v18
	v_fma_f32 v19, v27, v205, v19
	v_fma_f32 v16, v28, v206, v16
	v_fma_f32 v17, v29, v207, v17
	v_fma_f32 v18, v30, v208, v18
	v_fma_f32 v19, v31, v209, v19
	v_add_f32_e32 v20, v20, v21
	v_mfma_f32_32x32x2_f32 v[0:15], v210, v178, v[0:15]
	v_add_f32_e32 v21, v22, v23
	v_add_f32_e32 v16, v16, v17
	v_add_f32_e32 v17, v18, v19
	v_add_f32_e32 v20, v20, v21
	v_add_f32_e32 v16, v16, v17
	v_add_f32_e32 v16, v20, v16
	v_mov_b32_e32 v18, v16
	s_nop 1
	v_permlane32_swap_b32_e32 v16, v18
	s_and_saveexec_b64 s[28:29], s[6:7]
	s_cbranch_execz .LBB0_505
	s_add_i32 s39, s26, 1
	s_add_i32 s41, s30, 38
	s_and_b64 s[34:35], s[8:9], exec
	s_cselect_b32 s34, s39, s41
	s_waitcnt lgkmcnt(0)
	v_mul_f32_e32 v19, v161, v194
	v_mul_f32_e32 v17, v159, v195
	v_pk_add_f32 v[16:17], v[16:17], v[18:19]
	s_ashr_i32 s35, s34, 31
	v_add_f32_e32 v18, v16, v17
	v_lshl_add_u64 v[16:17], v[66:67], 0, s[34:35]
	v_lshlrev_b64 v[16:17], 11, v[16:17]
	v_lshl_add_u64 v[16:17], v[68:69], 0, v[16:17]
	global_store_dword v[16:17], v18, off
.LBB0_505:
	s_or_b64 exec, exec, s[28:29]
	ds_read_b128 v[18:21], v59 offset:2560
	ds_read_b128 v[22:25], v59 offset:2592
	ds_read_b128 v[26:29], v59 offset:3328
	ds_read_b128 v[162:165], v59 offset:3360
	ds_read_b128 v[166:169], v59 offset:2624
	ds_read_b128 v[170:173], v59 offset:2656
	ds_read_b128 v[174:177], v59 offset:3392
	ds_read_b128 v[178:181], v59 offset:3424
	ds_read_b128 v[182:185], v59 offset:2688
	ds_read_b128 v[186:189], v59 offset:2720
	ds_read_b128 v[190:193], v59 offset:2752
	ds_read_b128 v[194:197], v59 offset:2784
	s_waitcnt lgkmcnt(11)
	v_mul_f32_e32 v20, v2, v20
	v_mul_f32_e32 v21, v3, v21
	v_mul_f32_e32 v18, v0, v18
	v_mul_f32_e32 v19, v1, v19
	s_waitcnt lgkmcnt(3)
	v_mul_f32_e32 v30, v34, v184
	v_mul_f32_e32 v31, v35, v185
	v_mul_f32_e32 v182, v32, v182
	v_mul_f32_e32 v183, v33, v183
	v_fma_f32 v20, v6, v24, v20
	v_fma_f32 v21, v7, v25, v21
	v_fma_f32 v18, v4, v22, v18
	v_fma_f32 v19, v5, v23, v19
	s_waitcnt lgkmcnt(2)
	v_fma_f32 v22, v38, v188, v30
	v_fma_f32 v23, v39, v189, v31
	v_fma_f32 v24, v36, v186, v182
	v_fma_f32 v25, v37, v187, v183
	v_fma_f32 v18, v8, v166, v18
	v_fma_f32 v19, v9, v167, v19
	v_fma_f32 v20, v10, v168, v20
	v_fma_f32 v21, v11, v169, v21
	s_waitcnt lgkmcnt(1)
	v_fma_f32 v22, v42, v192, v22
	v_fma_f32 v23, v43, v193, v23
	v_add_u32_e32 v16, 0x800, v61
	v_fma_f32 v24, v40, v190, v24
	v_fma_f32 v25, v41, v191, v25
	v_fma_f32 v20, v14, v172, v20
	v_fma_f32 v21, v15, v173, v21
	v_fma_f32 v18, v12, v170, v18
	v_fma_f32 v19, v13, v171, v19
	s_waitcnt lgkmcnt(0)
	v_fma_f32 v22, v46, v196, v22
	v_fma_f32 v23, v47, v197, v23
	ds_read2_b32 v[198:199], v16 offset0:192 offset1:224
	ds_read_b32 v17, v158 offset:3584
	ds_read_b64 v[170:171], v50 offset:20752
	v_fma_f32 v24, v44, v194, v24
	v_fma_f32 v25, v45, v195, v25
	v_add_f32_e32 v16, v18, v19
	v_add_f32_e32 v18, v20, v21
	v_add_f32_e32 v19, v22, v23
	v_mul_f32_e32 v20, v2, v28
	v_mul_f32_e32 v21, v3, v29
	v_mul_f32_e32 v22, v0, v26
	v_mul_f32_e32 v23, v1, v27
	v_add_f32_e32 v16, v16, v18
	v_add_f32_e32 v18, v24, v25
	v_fma_f32 v20, v6, v164, v20
	v_fma_f32 v21, v7, v165, v21
	v_fma_f32 v22, v4, v162, v22
	v_fma_f32 v23, v5, v163, v23
	v_add_f32_e32 v18, v18, v19
	v_fma_f32 v22, v8, v174, v22
	v_fma_f32 v23, v9, v175, v23
	v_fma_f32 v20, v10, v176, v20
	v_fma_f32 v21, v11, v177, v21
	v_add_f32_e32 v16, v16, v18
	v_fma_f32 v166, v14, v180, v20
	v_fma_f32 v167, v15, v181, v21
	v_fma_f32 v168, v12, v178, v22
	v_fma_f32 v169, v13, v179, v23
	ds_read_b128 v[20:23], v59 offset:3456
	ds_read_b128 v[24:27], v59 offset:3488
	ds_read_b128 v[28:31], v59 offset:3520
	ds_read_b128 v[162:165], v59 offset:3552
	v_mov_b32_e32 v18, v16
	s_nop 1
	v_permlane32_swap_b32_e32 v16, v18
	s_waitcnt lgkmcnt(3)
	v_mul_f32_e32 v22, v34, v22
	v_mul_f32_e32 v23, v35, v23
	v_mul_f32_e32 v20, v32, v20
	v_mul_f32_e32 v21, v33, v21
	v_add_f32_e32 v19, v16, v18
	s_waitcnt lgkmcnt(2)
	v_fma_f32 v22, v38, v26, v22
	v_fma_f32 v23, v39, v27, v23
	v_fma_f32 v20, v36, v24, v20
	v_fma_f32 v21, v37, v25, v21
	v_cndmask_b32_e64 v16, v17, v19, s[6:7]
	s_waitcnt lgkmcnt(1)
	v_fma_f32 v20, v40, v28, v20
	v_fma_f32 v21, v41, v29, v21
	v_fma_f32 v22, v42, v30, v22
	v_fma_f32 v23, v43, v31, v23
	v_mfma_f32_32x32x2_f32 v[0:15], v198, v16, v[0:15]
	s_waitcnt lgkmcnt(0)
	v_fma_f32 v22, v46, v164, v22
	v_fma_f32 v23, v47, v165, v23
	v_fma_f32 v20, v44, v162, v20
	v_fma_f32 v21, v45, v163, v21
	v_add_f32_e32 v18, v166, v167
	v_mfma_f32_32x32x2_f32 v[32:47], v199, v16, v[32:47]
	v_add_f32_e32 v16, v168, v169
	v_add_f32_e32 v16, v16, v18
	v_add_f32_e32 v18, v20, v21
	v_add_f32_e32 v20, v22, v23
	v_add_f32_e32 v18, v18, v20
	v_add_f32_e32 v16, v16, v18
	v_mov_b32_e32 v18, v16
	s_nop 1
	v_permlane32_swap_b32_e32 v16, v18
	s_and_saveexec_b64 s[28:29], s[6:7]
	s_cbranch_execz .LBB0_507
	s_add_i32 s39, s26, 2
	s_add_i32 s41, s30, 37
	s_and_b64 s[34:35], s[8:9], exec
	s_cselect_b32 s34, s39, s41
	s_waitcnt lgkmcnt(0)
	v_mul_f32_e32 v19, v19, v170
	v_mul_f32_e32 v17, v17, v171
	v_pk_add_f32 v[16:17], v[16:17], v[18:19]
	s_ashr_i32 s35, s34, 31
	v_add_f32_e32 v18, v16, v17
	v_lshl_add_u64 v[16:17], v[66:67], 0, s[34:35]
	v_lshlrev_b64 v[16:17], 11, v[16:17]
	v_lshl_add_u64 v[16:17], v[68:69], 0, v[16:17]
	global_store_dword v[16:17], v18, off
.LBB0_507:
	s_or_b64 exec, exec, s[28:29]
	ds_read_b128 v[16:19], v59 offset:3840
	ds_read_b128 v[20:23], v59 offset:3872
	ds_read_b128 v[162:165], v59 offset:4608
	ds_read_b128 v[166:169], v59 offset:4640
	ds_read_b128 v[24:27], v59 offset:3904
	ds_read_b128 v[28:31], v59 offset:3936
	ds_read_b128 v[170:173], v59 offset:4672
	ds_read_b128 v[174:177], v59 offset:4704
	ds_read_b128 v[178:181], v59 offset:3968
	ds_read_b128 v[182:185], v59 offset:4000
	ds_read_b128 v[186:189], v59 offset:4736
	ds_read_b128 v[190:193], v59 offset:4768
	ds_read_b128 v[194:197], v59 offset:4032
	ds_read_b128 v[198:201], v59 offset:4064
	ds_read_b128 v[202:205], v59 offset:4800
	ds_read_b128 v[206:209], v59 offset:4832
	s_waitcnt lgkmcnt(14)
	v_mul_f32_e32 v18, v2, v18
	v_mul_f32_e32 v19, v3, v19
	v_mul_f32_e32 v16, v0, v16
	v_mul_f32_e32 v17, v1, v17
	s_waitcnt lgkmcnt(7)
	v_mul_f32_e32 v180, v34, v180
	v_mul_f32_e32 v181, v35, v181
	v_mul_f32_e32 v178, v32, v178
	v_mul_f32_e32 v179, v33, v179
	v_fma_f32 v18, v6, v22, v18
	v_fma_f32 v19, v7, v23, v19
	v_fma_f32 v16, v4, v20, v16
	v_fma_f32 v17, v5, v21, v17
	s_waitcnt lgkmcnt(6)
	v_fma_f32 v20, v38, v184, v180
	v_fma_f32 v21, v39, v185, v181
	v_fma_f32 v22, v36, v182, v178
	v_fma_f32 v23, v37, v183, v179
	v_fma_f32 v16, v8, v24, v16
	v_fma_f32 v17, v9, v25, v17
	v_fma_f32 v18, v10, v26, v18
	v_fma_f32 v19, v11, v27, v19
	s_waitcnt lgkmcnt(3)
	v_fma_f32 v22, v40, v194, v22
	v_fma_f32 v23, v41, v195, v23
	v_fma_f32 v20, v42, v196, v20
	v_fma_f32 v21, v43, v197, v21
	v_fma_f32 v18, v14, v30, v18
	v_fma_f32 v19, v15, v31, v19
	v_fma_f32 v16, v12, v28, v16
	v_fma_f32 v17, v13, v29, v17
	s_waitcnt lgkmcnt(2)
	v_fma_f32 v20, v46, v200, v20
	v_fma_f32 v21, v47, v201, v21
	v_fma_f32 v22, v44, v198, v22
	v_fma_f32 v23, v45, v199, v23
	v_add_f32_e32 v16, v16, v17
	v_add_f32_e32 v17, v18, v19
	v_add_u32_e32 v159, 0x1000, v61
	v_add_f32_e32 v16, v16, v17
	v_add_f32_e32 v17, v22, v23
	v_add_f32_e32 v18, v20, v21
	ds_read2_b32 v[210:211], v159 offset1:32
	ds_read_b32 v159, v158 offset:4864
	ds_read_b64 v[194:195], v50 offset:20760
	v_add_f32_e32 v17, v17, v18
	v_add_f32_e32 v16, v16, v17
	v_mov_b32_e32 v17, v16
	s_nop 1
	v_permlane32_swap_b32_e32 v16, v17
	v_add_f32_e32 v161, v16, v17
	s_waitcnt lgkmcnt(0)
	v_cndmask_b32_e64 v178, v159, v161, s[6:7]
	v_mul_f32_e32 v164, v2, v164
	v_mul_f32_e32 v165, v3, v165
	v_mul_f32_e32 v162, v0, v162
	v_mul_f32_e32 v163, v1, v163
	v_mfma_f32_32x32x2_f32 v[16:31], v211, v178, v[32:47]
	v_fma_f32 v34, v34, v188, 0
	v_fma_f32 v35, v35, v189, 0
	v_fma_f32 v32, v32, v186, 0
	v_fma_f32 v33, v33, v187, 0
	v_fma_f32 v164, v6, v168, v164
	v_fma_f32 v165, v7, v169, v165
	v_fma_f32 v162, v4, v166, v162
	v_fma_f32 v163, v5, v167, v163
	v_fma_f32 v34, v38, v192, v34
	v_fma_f32 v35, v39, v193, v35
	v_fma_f32 v32, v36, v190, v32
	v_fma_f32 v33, v37, v191, v33
	v_fma_f32 v36, v8, v170, v162
	v_fma_f32 v37, v9, v171, v163
	v_fma_f32 v38, v10, v172, v164
	v_fma_f32 v39, v11, v173, v165
	v_fma_f32 v36, v12, v174, v36
	v_fma_f32 v37, v13, v175, v37
	v_fma_f32 v38, v14, v176, v38
	v_fma_f32 v39, v15, v177, v39
	v_fma_f32 v32, v40, v202, v32
	v_fma_f32 v33, v41, v203, v33
	v_fma_f32 v34, v42, v204, v34
	v_fma_f32 v35, v43, v205, v35
	v_fma_f32 v32, v44, v206, v32
	v_fma_f32 v33, v45, v207, v33
	v_fma_f32 v34, v46, v208, v34
	v_fma_f32 v35, v47, v209, v35
	v_add_f32_e32 v36, v36, v37
	v_mfma_f32_32x32x2_f32 v[0:15], v210, v178, v[0:15]
	v_add_f32_e32 v37, v38, v39
	v_add_f32_e32 v32, v32, v33
	v_add_f32_e32 v33, v34, v35
	v_add_f32_e32 v36, v36, v37
	v_add_f32_e32 v32, v32, v33
	v_add_f32_e32 v32, v36, v32
	v_mov_b32_e32 v34, v32
	s_nop 1
	v_permlane32_swap_b32_e32 v32, v34
	s_and_saveexec_b64 s[28:29], s[6:7]
	s_cbranch_execz .LBB0_509
	s_add_i32 s39, s26, 3
	s_add_i32 s41, s30, 36
	s_and_b64 s[34:35], s[8:9], exec
	s_cselect_b32 s34, s39, s41
	s_waitcnt lgkmcnt(0)
	v_mul_f32_e32 v35, v161, v194
	v_mul_f32_e32 v33, v159, v195
	v_pk_add_f32 v[32:33], v[32:33], v[34:35]
	s_ashr_i32 s35, s34, 31
	v_add_f32_e32 v34, v32, v33
	v_lshl_add_u64 v[32:33], v[66:67], 0, s[34:35]
	v_lshlrev_b64 v[32:33], 11, v[32:33]
	v_lshl_add_u64 v[32:33], v[68:69], 0, v[32:33]
	global_store_dword v[32:33], v34, off
.LBB0_509:
	s_or_b64 exec, exec, s[28:29]
	ds_read_b128 v[34:37], v59 offset:5120
	ds_read_b128 v[38:41], v59 offset:5152
	ds_read_b128 v[42:45], v59 offset:5888
	ds_read_b128 v[162:165], v59 offset:5920
	ds_read_b128 v[166:169], v59 offset:5184
	ds_read_b128 v[170:173], v59 offset:5216
	ds_read_b128 v[174:177], v59 offset:5952
	ds_read_b128 v[178:181], v59 offset:5984
	ds_read_b128 v[182:185], v59 offset:5248
	ds_read_b128 v[186:189], v59 offset:5280
	ds_read_b128 v[190:193], v59 offset:5312
	ds_read_b128 v[194:197], v59 offset:5344
	s_waitcnt lgkmcnt(11)
	v_mul_f32_e32 v36, v2, v36
	v_mul_f32_e32 v37, v3, v37
	v_mul_f32_e32 v34, v0, v34
	v_mul_f32_e32 v35, v1, v35
	s_waitcnt lgkmcnt(3)
	v_mul_f32_e32 v46, v18, v184
	v_mul_f32_e32 v47, v19, v185
	v_mul_f32_e32 v182, v16, v182
	v_mul_f32_e32 v183, v17, v183
	v_fma_f32 v36, v6, v40, v36
	v_fma_f32 v37, v7, v41, v37
	v_fma_f32 v34, v4, v38, v34
	v_fma_f32 v35, v5, v39, v35
	s_waitcnt lgkmcnt(2)
	v_fma_f32 v38, v22, v188, v46
	v_fma_f32 v39, v23, v189, v47
	v_fma_f32 v40, v20, v186, v182
	v_fma_f32 v41, v21, v187, v183
	v_fma_f32 v34, v8, v166, v34
	v_fma_f32 v35, v9, v167, v35
	v_fma_f32 v36, v10, v168, v36
	v_fma_f32 v37, v11, v169, v37
	s_waitcnt lgkmcnt(1)
	v_fma_f32 v38, v26, v192, v38
	v_fma_f32 v39, v27, v193, v39
	v_add_u32_e32 v32, 0x1400, v61
	v_fma_f32 v40, v24, v190, v40
	v_fma_f32 v41, v25, v191, v41
	v_fma_f32 v36, v14, v172, v36
	v_fma_f32 v37, v15, v173, v37
	v_fma_f32 v34, v12, v170, v34
	v_fma_f32 v35, v13, v171, v35
	s_waitcnt lgkmcnt(0)
	v_fma_f32 v38, v30, v196, v38
	v_fma_f32 v39, v31, v197, v39
	ds_read2_b32 v[198:199], v32 offset0:64 offset1:96
	ds_read_b32 v33, v158 offset:6144
	ds_read_b64 v[170:171], v50 offset:20768
	v_fma_f32 v40, v28, v194, v40
	v_fma_f32 v41, v29, v195, v41
	v_add_f32_e32 v32, v34, v35
	v_add_f32_e32 v34, v36, v37
	v_add_f32_e32 v35, v38, v39
	v_mul_f32_e32 v36, v2, v44
	v_mul_f32_e32 v37, v3, v45
	v_mul_f32_e32 v38, v0, v42
	v_mul_f32_e32 v39, v1, v43
	v_add_f32_e32 v32, v32, v34
	v_add_f32_e32 v34, v40, v41
	v_fma_f32 v36, v6, v164, v36
	v_fma_f32 v37, v7, v165, v37
	v_fma_f32 v38, v4, v162, v38
	v_fma_f32 v39, v5, v163, v39
	v_add_f32_e32 v34, v34, v35
	v_fma_f32 v38, v8, v174, v38
	v_fma_f32 v39, v9, v175, v39
	v_fma_f32 v36, v10, v176, v36
	v_fma_f32 v37, v11, v177, v37
	v_add_f32_e32 v32, v32, v34
	v_fma_f32 v166, v14, v180, v36
	v_fma_f32 v167, v15, v181, v37
	v_fma_f32 v168, v12, v178, v38
	v_fma_f32 v169, v13, v179, v39
	ds_read_b128 v[36:39], v59 offset:6016
	ds_read_b128 v[40:43], v59 offset:6048
	ds_read_b128 v[44:47], v59 offset:6080
	ds_read_b128 v[162:165], v59 offset:6112
	v_mov_b32_e32 v34, v32
	s_nop 1
	v_permlane32_swap_b32_e32 v32, v34
	s_waitcnt lgkmcnt(3)
	v_mul_f32_e32 v38, v18, v38
	v_mul_f32_e32 v39, v19, v39
	v_mul_f32_e32 v36, v16, v36
	v_mul_f32_e32 v37, v17, v37
	v_add_f32_e32 v35, v32, v34
	s_waitcnt lgkmcnt(2)
	v_fma_f32 v38, v22, v42, v38
	v_fma_f32 v39, v23, v43, v39
	v_fma_f32 v36, v20, v40, v36
	v_fma_f32 v37, v21, v41, v37
	v_cndmask_b32_e64 v32, v33, v35, s[6:7]
	s_waitcnt lgkmcnt(1)
	v_fma_f32 v36, v24, v44, v36
	v_fma_f32 v37, v25, v45, v37
	v_fma_f32 v38, v26, v46, v38
	v_fma_f32 v39, v27, v47, v39
	v_mfma_f32_32x32x2_f32 v[0:15], v198, v32, v[0:15]
	s_waitcnt lgkmcnt(0)
	v_fma_f32 v38, v30, v164, v38
	v_fma_f32 v39, v31, v165, v39
	v_fma_f32 v36, v28, v162, v36
	v_fma_f32 v37, v29, v163, v37
	v_add_f32_e32 v34, v166, v167
	v_mfma_f32_32x32x2_f32 v[16:31], v199, v32, v[16:31]
	v_add_f32_e32 v32, v168, v169
	v_add_f32_e32 v32, v32, v34
	v_add_f32_e32 v34, v36, v37
	v_add_f32_e32 v36, v38, v39
	v_add_f32_e32 v34, v34, v36
	v_add_f32_e32 v32, v32, v34
	v_mov_b32_e32 v34, v32
	s_nop 1
	v_permlane32_swap_b32_e32 v32, v34
	s_and_saveexec_b64 s[28:29], s[6:7]
	s_cbranch_execz .LBB0_511
	s_add_i32 s39, s26, 4
	s_add_i32 s41, s30, 35
	s_and_b64 s[34:35], s[8:9], exec
	s_cselect_b32 s34, s39, s41
	s_waitcnt lgkmcnt(0)
	v_mul_f32_e32 v35, v35, v170
	v_mul_f32_e32 v33, v33, v171
	v_pk_add_f32 v[32:33], v[32:33], v[34:35]
	s_ashr_i32 s35, s34, 31
	v_add_f32_e32 v34, v32, v33
	v_lshl_add_u64 v[32:33], v[66:67], 0, s[34:35]
	v_lshlrev_b64 v[32:33], 11, v[32:33]
	v_lshl_add_u64 v[32:33], v[68:69], 0, v[32:33]
	global_store_dword v[32:33], v34, off
.LBB0_511:
	s_or_b64 exec, exec, s[28:29]
	ds_read_b128 v[32:35], v59 offset:6400
	ds_read_b128 v[36:39], v59 offset:6432
	ds_read_b128 v[162:165], v59 offset:7168
	ds_read_b128 v[166:169], v59 offset:7200
	ds_read_b128 v[40:43], v59 offset:6464
	ds_read_b128 v[44:47], v59 offset:6496
	ds_read_b128 v[170:173], v59 offset:7232
	ds_read_b128 v[174:177], v59 offset:7264
	ds_read_b128 v[178:181], v59 offset:6528
	ds_read_b128 v[182:185], v59 offset:6560
	ds_read_b128 v[186:189], v59 offset:7296
	ds_read_b128 v[190:193], v59 offset:7328
	ds_read_b128 v[194:197], v59 offset:6592
	ds_read_b128 v[198:201], v59 offset:6624
	ds_read_b128 v[202:205], v59 offset:7360
	ds_read_b128 v[206:209], v59 offset:7392
	s_waitcnt lgkmcnt(14)
	v_mul_f32_e32 v34, v2, v34
	v_mul_f32_e32 v35, v3, v35
	v_mul_f32_e32 v32, v0, v32
	v_mul_f32_e32 v33, v1, v33
	s_waitcnt lgkmcnt(7)
	v_mul_f32_e32 v180, v18, v180
	v_mul_f32_e32 v181, v19, v181
	v_mul_f32_e32 v178, v16, v178
	v_mul_f32_e32 v179, v17, v179
	v_fma_f32 v34, v6, v38, v34
	v_fma_f32 v35, v7, v39, v35
	v_fma_f32 v32, v4, v36, v32
	v_fma_f32 v33, v5, v37, v33
	s_waitcnt lgkmcnt(6)
	v_fma_f32 v36, v22, v184, v180
	v_fma_f32 v37, v23, v185, v181
	v_fma_f32 v38, v20, v182, v178
	v_fma_f32 v39, v21, v183, v179
	v_fma_f32 v32, v8, v40, v32
	v_fma_f32 v33, v9, v41, v33
	v_fma_f32 v34, v10, v42, v34
	v_fma_f32 v35, v11, v43, v35
	s_waitcnt lgkmcnt(3)
	v_fma_f32 v38, v24, v194, v38
	v_fma_f32 v39, v25, v195, v39
	v_fma_f32 v36, v26, v196, v36
	v_fma_f32 v37, v27, v197, v37
	v_fma_f32 v34, v14, v46, v34
	v_fma_f32 v35, v15, v47, v35
	v_fma_f32 v32, v12, v44, v32
	v_fma_f32 v33, v13, v45, v33
	s_waitcnt lgkmcnt(2)
	v_fma_f32 v36, v30, v200, v36
	v_fma_f32 v37, v31, v201, v37
	v_fma_f32 v38, v28, v198, v38
	v_fma_f32 v39, v29, v199, v39
	v_add_f32_e32 v32, v32, v33
	v_add_f32_e32 v33, v34, v35
	v_add_u32_e32 v159, 0x1800, v61
	v_add_f32_e32 v32, v32, v33
	v_add_f32_e32 v33, v38, v39
	v_add_f32_e32 v34, v36, v37
	ds_read2_b32 v[210:211], v159 offset0:128 offset1:160
	ds_read_b32 v159, v158 offset:7424
	ds_read_b64 v[194:195], v50 offset:20776
	v_add_f32_e32 v33, v33, v34
	v_add_f32_e32 v32, v32, v33
	v_mov_b32_e32 v33, v32
	s_nop 1
	v_permlane32_swap_b32_e32 v32, v33
	v_add_f32_e32 v161, v32, v33
	s_waitcnt lgkmcnt(0)
	v_cndmask_b32_e64 v178, v159, v161, s[6:7]
	v_mul_f32_e32 v164, v2, v164
	v_mul_f32_e32 v165, v3, v165
	v_mul_f32_e32 v162, v0, v162
	v_mul_f32_e32 v163, v1, v163
	v_mfma_f32_32x32x2_f32 v[32:47], v211, v178, v[16:31]
	v_fma_f32 v18, v18, v188, 0
	v_fma_f32 v19, v19, v189, 0
	v_fma_f32 v16, v16, v186, 0
	v_fma_f32 v17, v17, v187, 0
	v_fma_f32 v164, v6, v168, v164
	v_fma_f32 v165, v7, v169, v165
	v_fma_f32 v162, v4, v166, v162
	v_fma_f32 v163, v5, v167, v163
	v_fma_f32 v18, v22, v192, v18
	v_fma_f32 v19, v23, v193, v19
	v_fma_f32 v16, v20, v190, v16
	v_fma_f32 v17, v21, v191, v17
	v_fma_f32 v20, v8, v170, v162
	v_fma_f32 v21, v9, v171, v163
	v_fma_f32 v22, v10, v172, v164
	v_fma_f32 v23, v11, v173, v165
	v_fma_f32 v20, v12, v174, v20
	v_fma_f32 v21, v13, v175, v21
	v_fma_f32 v22, v14, v176, v22
	v_fma_f32 v23, v15, v177, v23
	v_fma_f32 v16, v24, v202, v16
	v_fma_f32 v17, v25, v203, v17
	v_fma_f32 v18, v26, v204, v18
	v_fma_f32 v19, v27, v205, v19
	v_fma_f32 v16, v28, v206, v16
	v_fma_f32 v17, v29, v207, v17
	v_fma_f32 v18, v30, v208, v18
	v_fma_f32 v19, v31, v209, v19
	v_add_f32_e32 v20, v20, v21
	v_mfma_f32_32x32x2_f32 v[0:15], v210, v178, v[0:15]
	v_add_f32_e32 v21, v22, v23
	v_add_f32_e32 v16, v16, v17
	v_add_f32_e32 v17, v18, v19
	v_add_f32_e32 v20, v20, v21
	v_add_f32_e32 v16, v16, v17
	v_add_f32_e32 v16, v20, v16
	v_mov_b32_e32 v18, v16
	s_nop 1
	v_permlane32_swap_b32_e32 v16, v18
	s_and_saveexec_b64 s[28:29], s[6:7]
	s_cbranch_execz .LBB0_513
	s_add_i32 s39, s26, 5
	s_add_i32 s41, s30, 34
	s_and_b64 s[34:35], s[8:9], exec
	s_cselect_b32 s34, s39, s41
	s_waitcnt lgkmcnt(0)
	v_mul_f32_e32 v19, v161, v194
	v_mul_f32_e32 v17, v159, v195
	v_pk_add_f32 v[16:17], v[16:17], v[18:19]
	s_ashr_i32 s35, s34, 31
	v_add_f32_e32 v18, v16, v17
	v_lshl_add_u64 v[16:17], v[66:67], 0, s[34:35]
	v_lshlrev_b64 v[16:17], 11, v[16:17]
	v_lshl_add_u64 v[16:17], v[68:69], 0, v[16:17]
	global_store_dword v[16:17], v18, off
.LBB0_513:
	s_or_b64 exec, exec, s[28:29]
	ds_read_b128 v[18:21], v59 offset:7680
	ds_read_b128 v[22:25], v59 offset:7712
	ds_read_b128 v[26:29], v59 offset:8448
	ds_read_b128 v[162:165], v59 offset:8480
	ds_read_b128 v[166:169], v59 offset:7744
	ds_read_b128 v[170:173], v59 offset:7776
	ds_read_b128 v[174:177], v59 offset:8512
	ds_read_b128 v[178:181], v59 offset:8544
	ds_read_b128 v[182:185], v59 offset:7808
	ds_read_b128 v[186:189], v59 offset:7840
	ds_read_b128 v[190:193], v59 offset:7872
	ds_read_b128 v[194:197], v59 offset:7904
	s_waitcnt lgkmcnt(11)
	v_mul_f32_e32 v20, v2, v20
	v_mul_f32_e32 v21, v3, v21
	v_mul_f32_e32 v18, v0, v18
	v_mul_f32_e32 v19, v1, v19
	s_waitcnt lgkmcnt(3)
	v_mul_f32_e32 v30, v34, v184
	v_mul_f32_e32 v31, v35, v185
	v_mul_f32_e32 v182, v32, v182
	v_mul_f32_e32 v183, v33, v183
	v_fma_f32 v20, v6, v24, v20
	v_fma_f32 v21, v7, v25, v21
	v_fma_f32 v18, v4, v22, v18
	v_fma_f32 v19, v5, v23, v19
	s_waitcnt lgkmcnt(2)
	v_fma_f32 v22, v38, v188, v30
	v_fma_f32 v23, v39, v189, v31
	v_fma_f32 v24, v36, v186, v182
	v_fma_f32 v25, v37, v187, v183
	v_fma_f32 v18, v8, v166, v18
	v_fma_f32 v19, v9, v167, v19
	v_fma_f32 v20, v10, v168, v20
	v_fma_f32 v21, v11, v169, v21
	s_waitcnt lgkmcnt(1)
	v_fma_f32 v22, v42, v192, v22
	v_fma_f32 v23, v43, v193, v23
	v_add_u32_e32 v16, 0x1c00, v61
	v_fma_f32 v24, v40, v190, v24
	v_fma_f32 v25, v41, v191, v25
	v_fma_f32 v20, v14, v172, v20
	v_fma_f32 v21, v15, v173, v21
	v_fma_f32 v18, v12, v170, v18
	v_fma_f32 v19, v13, v171, v19
	s_waitcnt lgkmcnt(0)
	v_fma_f32 v22, v46, v196, v22
	v_fma_f32 v23, v47, v197, v23
	ds_read2_b32 v[198:199], v16 offset0:192 offset1:224
	ds_read_b32 v17, v158 offset:8704
	ds_read_b64 v[170:171], v50 offset:20784
	v_fma_f32 v24, v44, v194, v24
	v_fma_f32 v25, v45, v195, v25
	v_add_f32_e32 v16, v18, v19
	v_add_f32_e32 v18, v20, v21
	v_add_f32_e32 v19, v22, v23
	v_mul_f32_e32 v20, v2, v28
	v_mul_f32_e32 v21, v3, v29
	v_mul_f32_e32 v22, v0, v26
	v_mul_f32_e32 v23, v1, v27
	v_add_f32_e32 v16, v16, v18
	v_add_f32_e32 v18, v24, v25
	v_fma_f32 v20, v6, v164, v20
	v_fma_f32 v21, v7, v165, v21
	v_fma_f32 v22, v4, v162, v22
	v_fma_f32 v23, v5, v163, v23
	v_add_f32_e32 v18, v18, v19
	v_fma_f32 v22, v8, v174, v22
	v_fma_f32 v23, v9, v175, v23
	v_fma_f32 v20, v10, v176, v20
	v_fma_f32 v21, v11, v177, v21
	v_add_f32_e32 v16, v16, v18
	v_fma_f32 v166, v14, v180, v20
	v_fma_f32 v167, v15, v181, v21
	v_fma_f32 v168, v12, v178, v22
	v_fma_f32 v169, v13, v179, v23
	ds_read_b128 v[20:23], v59 offset:8576
	ds_read_b128 v[24:27], v59 offset:8608
	ds_read_b128 v[28:31], v59 offset:8640
	ds_read_b128 v[162:165], v59 offset:8672
	v_mov_b32_e32 v18, v16
	s_nop 1
	v_permlane32_swap_b32_e32 v16, v18
	s_waitcnt lgkmcnt(3)
	v_mul_f32_e32 v22, v34, v22
	v_mul_f32_e32 v23, v35, v23
	v_mul_f32_e32 v20, v32, v20
	v_mul_f32_e32 v21, v33, v21
	v_add_f32_e32 v19, v16, v18
	s_waitcnt lgkmcnt(2)
	v_fma_f32 v22, v38, v26, v22
	v_fma_f32 v23, v39, v27, v23
	v_fma_f32 v20, v36, v24, v20
	v_fma_f32 v21, v37, v25, v21
	v_cndmask_b32_e64 v16, v17, v19, s[6:7]
	s_waitcnt lgkmcnt(1)
	v_fma_f32 v20, v40, v28, v20
	v_fma_f32 v21, v41, v29, v21
	v_fma_f32 v22, v42, v30, v22
	v_fma_f32 v23, v43, v31, v23
	v_mfma_f32_32x32x2_f32 v[0:15], v198, v16, v[0:15]
	s_waitcnt lgkmcnt(0)
	v_fma_f32 v22, v46, v164, v22
	v_fma_f32 v23, v47, v165, v23
	v_fma_f32 v20, v44, v162, v20
	v_fma_f32 v21, v45, v163, v21
	v_add_f32_e32 v18, v166, v167
	v_mfma_f32_32x32x2_f32 v[32:47], v199, v16, v[32:47]
	v_add_f32_e32 v16, v168, v169
	v_add_f32_e32 v16, v16, v18
	v_add_f32_e32 v18, v20, v21
	v_add_f32_e32 v20, v22, v23
	v_add_f32_e32 v18, v18, v20
	v_add_f32_e32 v16, v16, v18
	v_mov_b32_e32 v18, v16
	s_nop 1
	v_permlane32_swap_b32_e32 v16, v18
	s_and_saveexec_b64 s[28:29], s[6:7]
	s_cbranch_execz .LBB0_515
	s_add_i32 s39, s26, 6
	s_add_i32 s41, s30, 33
	s_and_b64 s[34:35], s[8:9], exec
	s_cselect_b32 s34, s39, s41
	s_waitcnt lgkmcnt(0)
	v_mul_f32_e32 v19, v19, v170
	v_mul_f32_e32 v17, v17, v171
	v_pk_add_f32 v[16:17], v[16:17], v[18:19]
	s_ashr_i32 s35, s34, 31
	v_add_f32_e32 v18, v16, v17
	v_lshl_add_u64 v[16:17], v[66:67], 0, s[34:35]
	v_lshlrev_b64 v[16:17], 11, v[16:17]
	v_lshl_add_u64 v[16:17], v[68:69], 0, v[16:17]
	global_store_dword v[16:17], v18, off
.LBB0_515:
	s_or_b64 exec, exec, s[28:29]
	ds_read_b128 v[16:19], v59 offset:8960
	ds_read_b128 v[20:23], v59 offset:8992
	ds_read_b128 v[162:165], v59 offset:9728
	ds_read_b128 v[166:169], v59 offset:9760
	ds_read_b128 v[24:27], v59 offset:9024
	ds_read_b128 v[28:31], v59 offset:9056
	ds_read_b128 v[170:173], v59 offset:9792
	ds_read_b128 v[174:177], v59 offset:9824
	ds_read_b128 v[178:181], v59 offset:9088
	ds_read_b128 v[182:185], v59 offset:9120
	ds_read_b128 v[186:189], v59 offset:9856
	ds_read_b128 v[190:193], v59 offset:9888
	ds_read_b128 v[194:197], v59 offset:9152
	ds_read_b128 v[198:201], v59 offset:9184
	ds_read_b128 v[202:205], v59 offset:9920
	ds_read_b128 v[206:209], v59 offset:9952
	s_waitcnt lgkmcnt(14)
	v_mul_f32_e32 v18, v2, v18
	v_mul_f32_e32 v19, v3, v19
	v_mul_f32_e32 v16, v0, v16
	v_mul_f32_e32 v17, v1, v17
	s_waitcnt lgkmcnt(7)
	v_mul_f32_e32 v180, v34, v180
	v_mul_f32_e32 v181, v35, v181
	v_mul_f32_e32 v178, v32, v178
	v_mul_f32_e32 v179, v33, v179
	v_fma_f32 v18, v6, v22, v18
	v_fma_f32 v19, v7, v23, v19
	v_fma_f32 v16, v4, v20, v16
	v_fma_f32 v17, v5, v21, v17
	s_waitcnt lgkmcnt(6)
	v_fma_f32 v20, v38, v184, v180
	v_fma_f32 v21, v39, v185, v181
	v_fma_f32 v22, v36, v182, v178
	v_fma_f32 v23, v37, v183, v179
	v_fma_f32 v16, v8, v24, v16
	v_fma_f32 v17, v9, v25, v17
	v_fma_f32 v18, v10, v26, v18
	v_fma_f32 v19, v11, v27, v19
	s_waitcnt lgkmcnt(3)
	v_fma_f32 v22, v40, v194, v22
	v_fma_f32 v23, v41, v195, v23
	v_fma_f32 v20, v42, v196, v20
	v_fma_f32 v21, v43, v197, v21
	v_fma_f32 v18, v14, v30, v18
	v_fma_f32 v19, v15, v31, v19
	v_fma_f32 v16, v12, v28, v16
	v_fma_f32 v17, v13, v29, v17
	s_waitcnt lgkmcnt(2)
	v_fma_f32 v20, v46, v200, v20
	v_fma_f32 v21, v47, v201, v21
	v_fma_f32 v22, v44, v198, v22
	v_fma_f32 v23, v45, v199, v23
	v_add_f32_e32 v16, v16, v17
	v_add_f32_e32 v17, v18, v19
	v_add_u32_e32 v159, 0x2400, v61
	v_add_f32_e32 v16, v16, v17
	v_add_f32_e32 v17, v22, v23
	v_add_f32_e32 v18, v20, v21
	ds_read2_b32 v[210:211], v159 offset1:32
	ds_read_b32 v159, v158 offset:9984
	ds_read_b64 v[194:195], v50 offset:20792
	v_add_f32_e32 v17, v17, v18
	v_add_f32_e32 v16, v16, v17
	v_mov_b32_e32 v17, v16
	s_nop 1
	v_permlane32_swap_b32_e32 v16, v17
	v_add_f32_e32 v161, v16, v17
	s_waitcnt lgkmcnt(0)
	v_cndmask_b32_e64 v178, v159, v161, s[6:7]
	v_mul_f32_e32 v164, v2, v164
	v_mul_f32_e32 v165, v3, v165
	v_mul_f32_e32 v162, v0, v162
	v_mul_f32_e32 v163, v1, v163
	v_mfma_f32_32x32x2_f32 v[16:31], v211, v178, v[32:47]
	v_fma_f32 v34, v34, v188, 0
	v_fma_f32 v35, v35, v189, 0
	v_fma_f32 v32, v32, v186, 0
	v_fma_f32 v33, v33, v187, 0
	v_fma_f32 v164, v6, v168, v164
	v_fma_f32 v165, v7, v169, v165
	v_fma_f32 v162, v4, v166, v162
	v_fma_f32 v163, v5, v167, v163
	v_fma_f32 v34, v38, v192, v34
	v_fma_f32 v35, v39, v193, v35
	v_fma_f32 v32, v36, v190, v32
	v_fma_f32 v33, v37, v191, v33
	v_fma_f32 v36, v8, v170, v162
	v_fma_f32 v37, v9, v171, v163
	v_fma_f32 v38, v10, v172, v164
	v_fma_f32 v39, v11, v173, v165
	v_fma_f32 v36, v12, v174, v36
	v_fma_f32 v37, v13, v175, v37
	v_fma_f32 v38, v14, v176, v38
	v_fma_f32 v39, v15, v177, v39
	v_fma_f32 v32, v40, v202, v32
	v_fma_f32 v33, v41, v203, v33
	v_fma_f32 v34, v42, v204, v34
	v_fma_f32 v35, v43, v205, v35
	v_fma_f32 v32, v44, v206, v32
	v_fma_f32 v33, v45, v207, v33
	v_fma_f32 v34, v46, v208, v34
	v_fma_f32 v35, v47, v209, v35
	v_add_f32_e32 v36, v36, v37
	v_mfma_f32_32x32x2_f32 v[0:15], v210, v178, v[0:15]
	v_add_f32_e32 v37, v38, v39
	v_add_f32_e32 v32, v32, v33
	v_add_f32_e32 v33, v34, v35
	v_add_f32_e32 v36, v36, v37
	v_add_f32_e32 v32, v32, v33
	v_add_f32_e32 v32, v36, v32
	v_mov_b32_e32 v34, v32
	s_nop 1
	v_permlane32_swap_b32_e32 v32, v34
	s_and_saveexec_b64 s[28:29], s[6:7]
	s_cbranch_execz .LBB0_517
	s_add_i32 s39, s26, 7
	s_add_i32 s41, s30, 32
	s_and_b64 s[34:35], s[8:9], exec
	s_cselect_b32 s34, s39, s41
	s_waitcnt lgkmcnt(0)
	v_mul_f32_e32 v35, v161, v194
	v_mul_f32_e32 v33, v159, v195
	v_pk_add_f32 v[32:33], v[32:33], v[34:35]
	s_ashr_i32 s35, s34, 31
	v_add_f32_e32 v34, v32, v33
	v_lshl_add_u64 v[32:33], v[66:67], 0, s[34:35]
	v_lshlrev_b64 v[32:33], 11, v[32:33]
	v_lshl_add_u64 v[32:33], v[68:69], 0, v[32:33]
	global_store_dword v[32:33], v34, off
.LBB0_517:
	s_or_b64 exec, exec, s[28:29]
	ds_read_b128 v[34:37], v59 offset:10240
	ds_read_b128 v[38:41], v59 offset:10272
	ds_read_b128 v[42:45], v59 offset:11008
	ds_read_b128 v[162:165], v59 offset:11040
	ds_read_b128 v[166:169], v59 offset:10304
	ds_read_b128 v[170:173], v59 offset:10336
	ds_read_b128 v[174:177], v59 offset:11072
	ds_read_b128 v[178:181], v59 offset:11104
	ds_read_b128 v[182:185], v59 offset:10368
	ds_read_b128 v[186:189], v59 offset:10400
	ds_read_b128 v[190:193], v59 offset:10432
	ds_read_b128 v[194:197], v59 offset:10464
	s_waitcnt lgkmcnt(11)
	v_mul_f32_e32 v36, v2, v36
	v_mul_f32_e32 v37, v3, v37
	v_mul_f32_e32 v34, v0, v34
	v_mul_f32_e32 v35, v1, v35
	s_waitcnt lgkmcnt(3)
	v_mul_f32_e32 v46, v18, v184
	v_mul_f32_e32 v47, v19, v185
	v_mul_f32_e32 v182, v16, v182
	v_mul_f32_e32 v183, v17, v183
	v_fma_f32 v36, v6, v40, v36
	v_fma_f32 v37, v7, v41, v37
	v_fma_f32 v34, v4, v38, v34
	v_fma_f32 v35, v5, v39, v35
	s_waitcnt lgkmcnt(2)
	v_fma_f32 v38, v22, v188, v46
	v_fma_f32 v39, v23, v189, v47
	v_fma_f32 v40, v20, v186, v182
	v_fma_f32 v41, v21, v187, v183
	v_fma_f32 v34, v8, v166, v34
	v_fma_f32 v35, v9, v167, v35
	v_fma_f32 v36, v10, v168, v36
	v_fma_f32 v37, v11, v169, v37
	s_waitcnt lgkmcnt(1)
	v_fma_f32 v38, v26, v192, v38
	v_fma_f32 v39, v27, v193, v39
	v_add_u32_e32 v32, 0x2800, v61
	v_fma_f32 v40, v24, v190, v40
	v_fma_f32 v41, v25, v191, v41
	v_fma_f32 v36, v14, v172, v36
	v_fma_f32 v37, v15, v173, v37
	v_fma_f32 v34, v12, v170, v34
	v_fma_f32 v35, v13, v171, v35
	s_waitcnt lgkmcnt(0)
	v_fma_f32 v38, v30, v196, v38
	v_fma_f32 v39, v31, v197, v39
	ds_read2_b32 v[198:199], v32 offset0:64 offset1:96
	ds_read_b32 v33, v158 offset:11264
	ds_read_b64 v[170:171], v50 offset:20800
	v_fma_f32 v40, v28, v194, v40
	v_fma_f32 v41, v29, v195, v41
	v_add_f32_e32 v32, v34, v35
	v_add_f32_e32 v34, v36, v37
	v_add_f32_e32 v35, v38, v39
	v_mul_f32_e32 v36, v2, v44
	v_mul_f32_e32 v37, v3, v45
	v_mul_f32_e32 v38, v0, v42
	v_mul_f32_e32 v39, v1, v43
	v_add_f32_e32 v32, v32, v34
	v_add_f32_e32 v34, v40, v41
	v_fma_f32 v36, v6, v164, v36
	v_fma_f32 v37, v7, v165, v37
	v_fma_f32 v38, v4, v162, v38
	v_fma_f32 v39, v5, v163, v39
	v_add_f32_e32 v34, v34, v35
	v_fma_f32 v38, v8, v174, v38
	v_fma_f32 v39, v9, v175, v39
	v_fma_f32 v36, v10, v176, v36
	v_fma_f32 v37, v11, v177, v37
	v_add_f32_e32 v32, v32, v34
	v_fma_f32 v166, v14, v180, v36
	v_fma_f32 v167, v15, v181, v37
	v_fma_f32 v168, v12, v178, v38
	v_fma_f32 v169, v13, v179, v39
	ds_read_b128 v[36:39], v59 offset:11136
	ds_read_b128 v[40:43], v59 offset:11168
	ds_read_b128 v[44:47], v59 offset:11200
	ds_read_b128 v[162:165], v59 offset:11232
	v_mov_b32_e32 v34, v32
	s_nop 1
	v_permlane32_swap_b32_e32 v32, v34
	s_waitcnt lgkmcnt(3)
	v_mul_f32_e32 v38, v18, v38
	v_mul_f32_e32 v39, v19, v39
	v_mul_f32_e32 v36, v16, v36
	v_mul_f32_e32 v37, v17, v37
	v_add_f32_e32 v35, v32, v34
	s_waitcnt lgkmcnt(2)
	v_fma_f32 v38, v22, v42, v38
	v_fma_f32 v39, v23, v43, v39
	v_fma_f32 v36, v20, v40, v36
	v_fma_f32 v37, v21, v41, v37
	v_cndmask_b32_e64 v32, v33, v35, s[6:7]
	s_waitcnt lgkmcnt(1)
	v_fma_f32 v36, v24, v44, v36
	v_fma_f32 v37, v25, v45, v37
	v_fma_f32 v38, v26, v46, v38
	v_fma_f32 v39, v27, v47, v39
	v_mfma_f32_32x32x2_f32 v[0:15], v198, v32, v[0:15]
	s_waitcnt lgkmcnt(0)
	v_fma_f32 v38, v30, v164, v38
	v_fma_f32 v39, v31, v165, v39
	v_fma_f32 v36, v28, v162, v36
	v_fma_f32 v37, v29, v163, v37
	v_add_f32_e32 v34, v166, v167
	v_mfma_f32_32x32x2_f32 v[16:31], v199, v32, v[16:31]
	v_add_f32_e32 v32, v168, v169
	v_add_f32_e32 v32, v32, v34
	v_add_f32_e32 v34, v36, v37
	v_add_f32_e32 v36, v38, v39
	v_add_f32_e32 v34, v34, v36
	v_add_f32_e32 v32, v32, v34
	v_mov_b32_e32 v34, v32
	s_nop 1
	v_permlane32_swap_b32_e32 v32, v34
	s_and_saveexec_b64 s[28:29], s[6:7]
	s_cbranch_execz .LBB0_519
	s_add_i32 s39, s26, 8
	s_add_i32 s41, s30, 31
	s_and_b64 s[34:35], s[8:9], exec
	s_cselect_b32 s34, s39, s41
	s_waitcnt lgkmcnt(0)
	v_mul_f32_e32 v35, v35, v170
	v_mul_f32_e32 v33, v33, v171
	v_pk_add_f32 v[32:33], v[32:33], v[34:35]
	s_ashr_i32 s35, s34, 31
	v_add_f32_e32 v34, v32, v33
	v_lshl_add_u64 v[32:33], v[66:67], 0, s[34:35]
	v_lshlrev_b64 v[32:33], 11, v[32:33]
	v_lshl_add_u64 v[32:33], v[68:69], 0, v[32:33]
	global_store_dword v[32:33], v34, off
.LBB0_519:
	s_or_b64 exec, exec, s[28:29]
	ds_read_b128 v[32:35], v59 offset:11520
	ds_read_b128 v[36:39], v59 offset:11552
	ds_read_b128 v[162:165], v59 offset:12288
	ds_read_b128 v[166:169], v59 offset:12320
	ds_read_b128 v[40:43], v59 offset:11584
	ds_read_b128 v[44:47], v59 offset:11616
	ds_read_b128 v[170:173], v59 offset:12352
	ds_read_b128 v[174:177], v59 offset:12384
	ds_read_b128 v[178:181], v59 offset:11648
	ds_read_b128 v[182:185], v59 offset:11680
	ds_read_b128 v[186:189], v59 offset:12416
	ds_read_b128 v[190:193], v59 offset:12448
	ds_read_b128 v[194:197], v59 offset:11712
	ds_read_b128 v[198:201], v59 offset:11744
	ds_read_b128 v[202:205], v59 offset:12480
	ds_read_b128 v[206:209], v59 offset:12512
	s_waitcnt lgkmcnt(14)
	v_mul_f32_e32 v34, v2, v34
	v_mul_f32_e32 v35, v3, v35
	v_mul_f32_e32 v32, v0, v32
	v_mul_f32_e32 v33, v1, v33
	s_waitcnt lgkmcnt(7)
	v_mul_f32_e32 v180, v18, v180
	v_mul_f32_e32 v181, v19, v181
	v_mul_f32_e32 v178, v16, v178
	v_mul_f32_e32 v179, v17, v179
	v_fma_f32 v34, v6, v38, v34
	v_fma_f32 v35, v7, v39, v35
	v_fma_f32 v32, v4, v36, v32
	v_fma_f32 v33, v5, v37, v33
	s_waitcnt lgkmcnt(6)
	v_fma_f32 v36, v22, v184, v180
	v_fma_f32 v37, v23, v185, v181
	v_fma_f32 v38, v20, v182, v178
	v_fma_f32 v39, v21, v183, v179
	v_fma_f32 v32, v8, v40, v32
	v_fma_f32 v33, v9, v41, v33
	v_fma_f32 v34, v10, v42, v34
	v_fma_f32 v35, v11, v43, v35
	s_waitcnt lgkmcnt(3)
	v_fma_f32 v38, v24, v194, v38
	v_fma_f32 v39, v25, v195, v39
	v_fma_f32 v36, v26, v196, v36
	v_fma_f32 v37, v27, v197, v37
	v_fma_f32 v34, v14, v46, v34
	v_fma_f32 v35, v15, v47, v35
	v_fma_f32 v32, v12, v44, v32
	v_fma_f32 v33, v13, v45, v33
	s_waitcnt lgkmcnt(2)
	v_fma_f32 v36, v30, v200, v36
	v_fma_f32 v37, v31, v201, v37
	v_fma_f32 v38, v28, v198, v38
	v_fma_f32 v39, v29, v199, v39
	v_add_f32_e32 v32, v32, v33
	v_add_f32_e32 v33, v34, v35
	v_add_u32_e32 v159, 0x2c00, v61
	v_add_f32_e32 v32, v32, v33
	v_add_f32_e32 v33, v38, v39
	v_add_f32_e32 v34, v36, v37
	ds_read2_b32 v[210:211], v159 offset0:128 offset1:160
	ds_read_b32 v159, v158 offset:12544
	ds_read_b64 v[194:195], v50 offset:20808
	v_add_f32_e32 v33, v33, v34
	v_add_f32_e32 v32, v32, v33
	v_mov_b32_e32 v33, v32
	s_nop 1
	v_permlane32_swap_b32_e32 v32, v33
	v_add_f32_e32 v161, v32, v33
	s_waitcnt lgkmcnt(0)
	v_cndmask_b32_e64 v178, v159, v161, s[6:7]
	v_mul_f32_e32 v164, v2, v164
	v_mul_f32_e32 v165, v3, v165
	v_mul_f32_e32 v162, v0, v162
	v_mul_f32_e32 v163, v1, v163
	v_mfma_f32_32x32x2_f32 v[32:47], v211, v178, v[16:31]
	v_fma_f32 v18, v18, v188, 0
	v_fma_f32 v19, v19, v189, 0
	v_fma_f32 v16, v16, v186, 0
	v_fma_f32 v17, v17, v187, 0
	v_fma_f32 v164, v6, v168, v164
	v_fma_f32 v165, v7, v169, v165
	v_fma_f32 v162, v4, v166, v162
	v_fma_f32 v163, v5, v167, v163
	v_fma_f32 v18, v22, v192, v18
	v_fma_f32 v19, v23, v193, v19
	v_fma_f32 v16, v20, v190, v16
	v_fma_f32 v17, v21, v191, v17
	v_fma_f32 v20, v8, v170, v162
	v_fma_f32 v21, v9, v171, v163
	v_fma_f32 v22, v10, v172, v164
	v_fma_f32 v23, v11, v173, v165
	v_fma_f32 v20, v12, v174, v20
	v_fma_f32 v21, v13, v175, v21
	v_fma_f32 v22, v14, v176, v22
	v_fma_f32 v23, v15, v177, v23
	v_fma_f32 v16, v24, v202, v16
	v_fma_f32 v17, v25, v203, v17
	v_fma_f32 v18, v26, v204, v18
	v_fma_f32 v19, v27, v205, v19
	v_fma_f32 v16, v28, v206, v16
	v_fma_f32 v17, v29, v207, v17
	v_fma_f32 v18, v30, v208, v18
	v_fma_f32 v19, v31, v209, v19
	v_add_f32_e32 v20, v20, v21
	v_mfma_f32_32x32x2_f32 v[0:15], v210, v178, v[0:15]
	v_add_f32_e32 v21, v22, v23
	v_add_f32_e32 v16, v16, v17
	v_add_f32_e32 v17, v18, v19
	v_add_f32_e32 v20, v20, v21
	v_add_f32_e32 v16, v16, v17
	v_add_f32_e32 v16, v20, v16
	v_mov_b32_e32 v18, v16
	s_nop 1
	v_permlane32_swap_b32_e32 v16, v18
	s_and_saveexec_b64 s[28:29], s[6:7]
	s_cbranch_execz .LBB0_521
	s_add_i32 s39, s26, 9
	s_add_i32 s41, s30, 30
	s_and_b64 s[34:35], s[8:9], exec
	s_cselect_b32 s34, s39, s41
	s_waitcnt lgkmcnt(0)
	v_mul_f32_e32 v19, v161, v194
	v_mul_f32_e32 v17, v159, v195
	v_pk_add_f32 v[16:17], v[16:17], v[18:19]
	s_ashr_i32 s35, s34, 31
	v_add_f32_e32 v18, v16, v17
	v_lshl_add_u64 v[16:17], v[66:67], 0, s[34:35]
	v_lshlrev_b64 v[16:17], 11, v[16:17]
	v_lshl_add_u64 v[16:17], v[68:69], 0, v[16:17]
	global_store_dword v[16:17], v18, off
.LBB0_521:
	s_or_b64 exec, exec, s[28:29]
	ds_read_b128 v[18:21], v59 offset:12800
	ds_read_b128 v[22:25], v59 offset:12832
	ds_read_b128 v[26:29], v59 offset:13568
	ds_read_b128 v[162:165], v59 offset:13600
	ds_read_b128 v[166:169], v59 offset:12864
	ds_read_b128 v[170:173], v59 offset:12896
	ds_read_b128 v[174:177], v59 offset:13632
	ds_read_b128 v[178:181], v59 offset:13664
	ds_read_b128 v[182:185], v59 offset:12928
	ds_read_b128 v[186:189], v59 offset:12960
	ds_read_b128 v[190:193], v59 offset:12992
	ds_read_b128 v[194:197], v59 offset:13024
	s_waitcnt lgkmcnt(11)
	v_mul_f32_e32 v20, v2, v20
	v_mul_f32_e32 v21, v3, v21
	v_mul_f32_e32 v18, v0, v18
	v_mul_f32_e32 v19, v1, v19
	s_waitcnt lgkmcnt(3)
	v_mul_f32_e32 v30, v34, v184
	v_mul_f32_e32 v31, v35, v185
	v_mul_f32_e32 v182, v32, v182
	v_mul_f32_e32 v183, v33, v183
	v_fma_f32 v20, v6, v24, v20
	v_fma_f32 v21, v7, v25, v21
	v_fma_f32 v18, v4, v22, v18
	v_fma_f32 v19, v5, v23, v19
	s_waitcnt lgkmcnt(2)
	v_fma_f32 v22, v38, v188, v30
	v_fma_f32 v23, v39, v189, v31
	v_fma_f32 v24, v36, v186, v182
	v_fma_f32 v25, v37, v187, v183
	v_fma_f32 v18, v8, v166, v18
	v_fma_f32 v19, v9, v167, v19
	v_fma_f32 v20, v10, v168, v20
	v_fma_f32 v21, v11, v169, v21
	s_waitcnt lgkmcnt(1)
	v_fma_f32 v22, v42, v192, v22
	v_fma_f32 v23, v43, v193, v23
	v_add_u32_e32 v16, 0x3000, v61
	v_fma_f32 v24, v40, v190, v24
	v_fma_f32 v25, v41, v191, v25
	v_fma_f32 v20, v14, v172, v20
	v_fma_f32 v21, v15, v173, v21
	v_fma_f32 v18, v12, v170, v18
	v_fma_f32 v19, v13, v171, v19
	s_waitcnt lgkmcnt(0)
	v_fma_f32 v22, v46, v196, v22
	v_fma_f32 v23, v47, v197, v23
	ds_read2_b32 v[198:199], v16 offset0:192 offset1:224
	ds_read_b32 v17, v158 offset:13824
	ds_read_b64 v[170:171], v50 offset:20816
	v_fma_f32 v24, v44, v194, v24
	v_fma_f32 v25, v45, v195, v25
	v_add_f32_e32 v16, v18, v19
	v_add_f32_e32 v18, v20, v21
	v_add_f32_e32 v19, v22, v23
	v_mul_f32_e32 v20, v2, v28
	v_mul_f32_e32 v21, v3, v29
	v_mul_f32_e32 v22, v0, v26
	v_mul_f32_e32 v23, v1, v27
	v_add_f32_e32 v16, v16, v18
	v_add_f32_e32 v18, v24, v25
	v_fma_f32 v20, v6, v164, v20
	v_fma_f32 v21, v7, v165, v21
	v_fma_f32 v22, v4, v162, v22
	v_fma_f32 v23, v5, v163, v23
	v_add_f32_e32 v18, v18, v19
	v_fma_f32 v22, v8, v174, v22
	v_fma_f32 v23, v9, v175, v23
	v_fma_f32 v20, v10, v176, v20
	v_fma_f32 v21, v11, v177, v21
	v_add_f32_e32 v16, v16, v18
	v_fma_f32 v166, v14, v180, v20
	v_fma_f32 v167, v15, v181, v21
	v_fma_f32 v168, v12, v178, v22
	v_fma_f32 v169, v13, v179, v23
	ds_read_b128 v[20:23], v59 offset:13696
	ds_read_b128 v[24:27], v59 offset:13728
	ds_read_b128 v[28:31], v59 offset:13760
	ds_read_b128 v[162:165], v59 offset:13792
	v_mov_b32_e32 v18, v16
	s_nop 1
	v_permlane32_swap_b32_e32 v16, v18
	s_waitcnt lgkmcnt(3)
	v_mul_f32_e32 v22, v34, v22
	v_mul_f32_e32 v23, v35, v23
	v_mul_f32_e32 v20, v32, v20
	v_mul_f32_e32 v21, v33, v21
	v_add_f32_e32 v19, v16, v18
	s_waitcnt lgkmcnt(2)
	v_fma_f32 v22, v38, v26, v22
	v_fma_f32 v23, v39, v27, v23
	v_fma_f32 v20, v36, v24, v20
	v_fma_f32 v21, v37, v25, v21
	v_cndmask_b32_e64 v16, v17, v19, s[6:7]
	s_waitcnt lgkmcnt(1)
	v_fma_f32 v20, v40, v28, v20
	v_fma_f32 v21, v41, v29, v21
	v_fma_f32 v22, v42, v30, v22
	v_fma_f32 v23, v43, v31, v23
	v_mfma_f32_32x32x2_f32 v[0:15], v198, v16, v[0:15]
	s_waitcnt lgkmcnt(0)
	v_fma_f32 v22, v46, v164, v22
	v_fma_f32 v23, v47, v165, v23
	v_fma_f32 v20, v44, v162, v20
	v_fma_f32 v21, v45, v163, v21
	v_add_f32_e32 v18, v166, v167
	v_mfma_f32_32x32x2_f32 v[32:47], v199, v16, v[32:47]
	v_add_f32_e32 v16, v168, v169
	v_add_f32_e32 v16, v16, v18
	v_add_f32_e32 v18, v20, v21
	v_add_f32_e32 v20, v22, v23
	v_add_f32_e32 v18, v18, v20
	v_add_f32_e32 v16, v16, v18
	v_mov_b32_e32 v18, v16
	s_nop 1
	v_permlane32_swap_b32_e32 v16, v18
	s_and_saveexec_b64 s[28:29], s[6:7]
	s_cbranch_execz .LBB0_523
	s_add_i32 s39, s26, 10
	s_add_i32 s41, s30, 29
	s_and_b64 s[34:35], s[8:9], exec
	s_cselect_b32 s34, s39, s41
	s_waitcnt lgkmcnt(0)
	v_mul_f32_e32 v19, v19, v170
	v_mul_f32_e32 v17, v17, v171
	v_pk_add_f32 v[16:17], v[16:17], v[18:19]
	s_ashr_i32 s35, s34, 31
	v_add_f32_e32 v18, v16, v17
	v_lshl_add_u64 v[16:17], v[66:67], 0, s[34:35]
	v_lshlrev_b64 v[16:17], 11, v[16:17]
	v_lshl_add_u64 v[16:17], v[68:69], 0, v[16:17]
	global_store_dword v[16:17], v18, off
.LBB0_523:
	s_or_b64 exec, exec, s[28:29]
	ds_read_b128 v[16:19], v59 offset:14080
	ds_read_b128 v[20:23], v59 offset:14112
	ds_read_b128 v[162:165], v59 offset:14848
	ds_read_b128 v[166:169], v59 offset:14880
	ds_read_b128 v[24:27], v59 offset:14144
	ds_read_b128 v[28:31], v59 offset:14176
	ds_read_b128 v[170:173], v59 offset:14912
	ds_read_b128 v[174:177], v59 offset:14944
	ds_read_b128 v[178:181], v59 offset:14208
	ds_read_b128 v[182:185], v59 offset:14240
	ds_read_b128 v[186:189], v59 offset:14976
	ds_read_b128 v[190:193], v59 offset:15008
	ds_read_b128 v[194:197], v59 offset:14272
	ds_read_b128 v[198:201], v59 offset:14304
	ds_read_b128 v[202:205], v59 offset:15040
	ds_read_b128 v[206:209], v59 offset:15072
	s_waitcnt lgkmcnt(14)
	v_mul_f32_e32 v18, v2, v18
	v_mul_f32_e32 v19, v3, v19
	v_mul_f32_e32 v16, v0, v16
	v_mul_f32_e32 v17, v1, v17
	s_waitcnt lgkmcnt(7)
	v_mul_f32_e32 v180, v34, v180
	v_mul_f32_e32 v181, v35, v181
	v_mul_f32_e32 v178, v32, v178
	v_mul_f32_e32 v179, v33, v179
	v_fma_f32 v18, v6, v22, v18
	v_fma_f32 v19, v7, v23, v19
	v_fma_f32 v16, v4, v20, v16
	v_fma_f32 v17, v5, v21, v17
	s_waitcnt lgkmcnt(6)
	v_fma_f32 v20, v38, v184, v180
	v_fma_f32 v21, v39, v185, v181
	v_fma_f32 v22, v36, v182, v178
	v_fma_f32 v23, v37, v183, v179
	v_fma_f32 v16, v8, v24, v16
	v_fma_f32 v17, v9, v25, v17
	v_fma_f32 v18, v10, v26, v18
	v_fma_f32 v19, v11, v27, v19
	s_waitcnt lgkmcnt(3)
	v_fma_f32 v22, v40, v194, v22
	v_fma_f32 v23, v41, v195, v23
	v_fma_f32 v20, v42, v196, v20
	v_fma_f32 v21, v43, v197, v21
	v_fma_f32 v18, v14, v30, v18
	v_fma_f32 v19, v15, v31, v19
	v_fma_f32 v16, v12, v28, v16
	v_fma_f32 v17, v13, v29, v17
	s_waitcnt lgkmcnt(2)
	v_fma_f32 v20, v46, v200, v20
	v_fma_f32 v21, v47, v201, v21
	v_fma_f32 v22, v44, v198, v22
	v_fma_f32 v23, v45, v199, v23
	v_add_f32_e32 v16, v16, v17
	v_add_f32_e32 v17, v18, v19
	v_add_u32_e32 v159, 0x3800, v61
	v_add_f32_e32 v16, v16, v17
	v_add_f32_e32 v17, v22, v23
	v_add_f32_e32 v18, v20, v21
	ds_read2_b32 v[210:211], v159 offset1:32
	ds_read_b32 v159, v158 offset:15104
	ds_read_b64 v[194:195], v50 offset:20824
	v_add_f32_e32 v17, v17, v18
	v_add_f32_e32 v16, v16, v17
	v_mov_b32_e32 v17, v16
	s_nop 1
	v_permlane32_swap_b32_e32 v16, v17
	v_add_f32_e32 v161, v16, v17
	s_waitcnt lgkmcnt(0)
	v_cndmask_b32_e64 v178, v159, v161, s[6:7]
	v_mul_f32_e32 v164, v2, v164
	v_mul_f32_e32 v165, v3, v165
	v_mul_f32_e32 v162, v0, v162
	v_mul_f32_e32 v163, v1, v163
	v_mfma_f32_32x32x2_f32 v[16:31], v211, v178, v[32:47]
	v_fma_f32 v34, v34, v188, 0
	v_fma_f32 v35, v35, v189, 0
	v_fma_f32 v32, v32, v186, 0
	v_fma_f32 v33, v33, v187, 0
	v_fma_f32 v164, v6, v168, v164
	v_fma_f32 v165, v7, v169, v165
	v_fma_f32 v162, v4, v166, v162
	v_fma_f32 v163, v5, v167, v163
	v_fma_f32 v34, v38, v192, v34
	v_fma_f32 v35, v39, v193, v35
	v_fma_f32 v32, v36, v190, v32
	v_fma_f32 v33, v37, v191, v33
	v_fma_f32 v36, v8, v170, v162
	v_fma_f32 v37, v9, v171, v163
	v_fma_f32 v38, v10, v172, v164
	v_fma_f32 v39, v11, v173, v165
	v_fma_f32 v36, v12, v174, v36
	v_fma_f32 v37, v13, v175, v37
	v_fma_f32 v38, v14, v176, v38
	v_fma_f32 v39, v15, v177, v39
	v_fma_f32 v32, v40, v202, v32
	v_fma_f32 v33, v41, v203, v33
	v_fma_f32 v34, v42, v204, v34
	v_fma_f32 v35, v43, v205, v35
	v_fma_f32 v32, v44, v206, v32
	v_fma_f32 v33, v45, v207, v33
	v_fma_f32 v34, v46, v208, v34
	v_fma_f32 v35, v47, v209, v35
	v_add_f32_e32 v36, v36, v37
	v_mfma_f32_32x32x2_f32 v[0:15], v210, v178, v[0:15]
	v_add_f32_e32 v37, v38, v39
	v_add_f32_e32 v32, v32, v33
	v_add_f32_e32 v33, v34, v35
	v_add_f32_e32 v36, v36, v37
	v_add_f32_e32 v32, v32, v33
	v_add_f32_e32 v32, v36, v32
	v_mov_b32_e32 v34, v32
	s_nop 1
	v_permlane32_swap_b32_e32 v32, v34
	s_and_saveexec_b64 s[28:29], s[6:7]
	s_cbranch_execz .LBB0_525
	s_add_i32 s39, s26, 11
	s_add_i32 s41, s30, 28
	s_and_b64 s[34:35], s[8:9], exec
	s_cselect_b32 s34, s39, s41
	s_waitcnt lgkmcnt(0)
	v_mul_f32_e32 v35, v161, v194
	v_mul_f32_e32 v33, v159, v195
	v_pk_add_f32 v[32:33], v[32:33], v[34:35]
	s_ashr_i32 s35, s34, 31
	v_add_f32_e32 v34, v32, v33
	v_lshl_add_u64 v[32:33], v[66:67], 0, s[34:35]
	v_lshlrev_b64 v[32:33], 11, v[32:33]
	v_lshl_add_u64 v[32:33], v[68:69], 0, v[32:33]
	global_store_dword v[32:33], v34, off
.LBB0_525:
	s_or_b64 exec, exec, s[28:29]
	ds_read_b128 v[34:37], v59 offset:15360
	ds_read_b128 v[38:41], v59 offset:15392
	ds_read_b128 v[42:45], v59 offset:16128
	ds_read_b128 v[162:165], v59 offset:16160
	ds_read_b128 v[166:169], v59 offset:15424
	ds_read_b128 v[170:173], v59 offset:15456
	ds_read_b128 v[174:177], v59 offset:16192
	ds_read_b128 v[178:181], v59 offset:16224
	ds_read_b128 v[182:185], v59 offset:15488
	ds_read_b128 v[186:189], v59 offset:15520
	ds_read_b128 v[190:193], v59 offset:15552
	ds_read_b128 v[194:197], v59 offset:15584
	s_waitcnt lgkmcnt(11)
	v_mul_f32_e32 v36, v2, v36
	v_mul_f32_e32 v37, v3, v37
	v_mul_f32_e32 v34, v0, v34
	v_mul_f32_e32 v35, v1, v35
	s_waitcnt lgkmcnt(3)
	v_mul_f32_e32 v46, v18, v184
	v_mul_f32_e32 v47, v19, v185
	v_mul_f32_e32 v182, v16, v182
	v_mul_f32_e32 v183, v17, v183
	v_fma_f32 v36, v6, v40, v36
	v_fma_f32 v37, v7, v41, v37
	v_fma_f32 v34, v4, v38, v34
	v_fma_f32 v35, v5, v39, v35
	s_waitcnt lgkmcnt(2)
	v_fma_f32 v38, v22, v188, v46
	v_fma_f32 v39, v23, v189, v47
	v_fma_f32 v40, v20, v186, v182
	v_fma_f32 v41, v21, v187, v183
	v_fma_f32 v34, v8, v166, v34
	v_fma_f32 v35, v9, v167, v35
	v_fma_f32 v36, v10, v168, v36
	v_fma_f32 v37, v11, v169, v37
	s_waitcnt lgkmcnt(1)
	v_fma_f32 v38, v26, v192, v38
	v_fma_f32 v39, v27, v193, v39
	v_add_u32_e32 v32, 0x3c00, v61
	v_fma_f32 v40, v24, v190, v40
	v_fma_f32 v41, v25, v191, v41
	v_fma_f32 v36, v14, v172, v36
	v_fma_f32 v37, v15, v173, v37
	v_fma_f32 v34, v12, v170, v34
	v_fma_f32 v35, v13, v171, v35
	s_waitcnt lgkmcnt(0)
	v_fma_f32 v38, v30, v196, v38
	v_fma_f32 v39, v31, v197, v39
	ds_read2_b32 v[198:199], v32 offset0:64 offset1:96
	ds_read_b32 v33, v158 offset:16384
	ds_read_b64 v[170:171], v50 offset:20832
	v_fma_f32 v40, v28, v194, v40
	v_fma_f32 v41, v29, v195, v41
	v_add_f32_e32 v32, v34, v35
	v_add_f32_e32 v34, v36, v37
	v_add_f32_e32 v35, v38, v39
	v_mul_f32_e32 v36, v2, v44
	v_mul_f32_e32 v37, v3, v45
	v_mul_f32_e32 v38, v0, v42
	v_mul_f32_e32 v39, v1, v43
	v_add_f32_e32 v32, v32, v34
	v_add_f32_e32 v34, v40, v41
	v_fma_f32 v36, v6, v164, v36
	v_fma_f32 v37, v7, v165, v37
	v_fma_f32 v38, v4, v162, v38
	v_fma_f32 v39, v5, v163, v39
	v_add_f32_e32 v34, v34, v35
	v_fma_f32 v38, v8, v174, v38
	v_fma_f32 v39, v9, v175, v39
	v_fma_f32 v36, v10, v176, v36
	v_fma_f32 v37, v11, v177, v37
	v_add_f32_e32 v32, v32, v34
	v_fma_f32 v166, v14, v180, v36
	v_fma_f32 v167, v15, v181, v37
	v_fma_f32 v168, v12, v178, v38
	v_fma_f32 v169, v13, v179, v39
	ds_read_b128 v[36:39], v59 offset:16256
	ds_read_b128 v[40:43], v59 offset:16288
	ds_read_b128 v[44:47], v59 offset:16320
	ds_read_b128 v[162:165], v59 offset:16352
	v_mov_b32_e32 v34, v32
	s_nop 1
	v_permlane32_swap_b32_e32 v32, v34
	s_waitcnt lgkmcnt(3)
	v_mul_f32_e32 v38, v18, v38
	v_mul_f32_e32 v39, v19, v39
	v_mul_f32_e32 v36, v16, v36
	v_mul_f32_e32 v37, v17, v37
	v_add_f32_e32 v35, v32, v34
	s_waitcnt lgkmcnt(2)
	v_fma_f32 v38, v22, v42, v38
	v_fma_f32 v39, v23, v43, v39
	v_fma_f32 v36, v20, v40, v36
	v_fma_f32 v37, v21, v41, v37
	v_cndmask_b32_e64 v32, v33, v35, s[6:7]
	s_waitcnt lgkmcnt(1)
	v_fma_f32 v36, v24, v44, v36
	v_fma_f32 v37, v25, v45, v37
	v_fma_f32 v38, v26, v46, v38
	v_fma_f32 v39, v27, v47, v39
	v_mfma_f32_32x32x2_f32 v[0:15], v198, v32, v[0:15]
	s_waitcnt lgkmcnt(0)
	v_fma_f32 v38, v30, v164, v38
	v_fma_f32 v39, v31, v165, v39
	v_fma_f32 v36, v28, v162, v36
	v_fma_f32 v37, v29, v163, v37
	v_add_f32_e32 v34, v166, v167
	v_mfma_f32_32x32x2_f32 v[16:31], v199, v32, v[16:31]
	v_add_f32_e32 v32, v168, v169
	v_add_f32_e32 v32, v32, v34
	v_add_f32_e32 v34, v36, v37
	v_add_f32_e32 v36, v38, v39
	v_add_f32_e32 v34, v34, v36
	v_add_f32_e32 v32, v32, v34
	v_mov_b32_e32 v34, v32
	s_nop 1
	v_permlane32_swap_b32_e32 v32, v34
	s_and_saveexec_b64 s[28:29], s[6:7]
	s_cbranch_execz .LBB0_527
	s_add_i32 s39, s26, 12
	s_add_i32 s41, s30, 27
	s_and_b64 s[34:35], s[8:9], exec
	s_cselect_b32 s34, s39, s41
	s_waitcnt lgkmcnt(0)
	v_mul_f32_e32 v35, v35, v170
	v_mul_f32_e32 v33, v33, v171
	v_pk_add_f32 v[32:33], v[32:33], v[34:35]
	s_ashr_i32 s35, s34, 31
	v_add_f32_e32 v34, v32, v33
	v_lshl_add_u64 v[32:33], v[66:67], 0, s[34:35]
	v_lshlrev_b64 v[32:33], 11, v[32:33]
	v_lshl_add_u64 v[32:33], v[68:69], 0, v[32:33]
	global_store_dword v[32:33], v34, off
.LBB0_527:
	s_or_b64 exec, exec, s[28:29]
	ds_read_b128 v[32:35], v59 offset:16640
	ds_read_b128 v[36:39], v59 offset:16672
	ds_read_b128 v[162:165], v59 offset:17408
	ds_read_b128 v[166:169], v59 offset:17440
	ds_read_b128 v[40:43], v59 offset:16704
	ds_read_b128 v[44:47], v59 offset:16736
	ds_read_b128 v[170:173], v59 offset:17472
	ds_read_b128 v[174:177], v59 offset:17504
	ds_read_b128 v[178:181], v59 offset:16768
	ds_read_b128 v[182:185], v59 offset:16800
	ds_read_b128 v[186:189], v59 offset:17536
	ds_read_b128 v[190:193], v59 offset:17568
	ds_read_b128 v[194:197], v59 offset:16832
	ds_read_b128 v[198:201], v59 offset:16864
	ds_read_b128 v[202:205], v59 offset:17600
	ds_read_b128 v[206:209], v59 offset:17632
	s_waitcnt lgkmcnt(14)
	v_mul_f32_e32 v34, v2, v34
	v_mul_f32_e32 v35, v3, v35
	v_mul_f32_e32 v32, v0, v32
	v_mul_f32_e32 v33, v1, v33
	s_waitcnt lgkmcnt(7)
	v_mul_f32_e32 v180, v18, v180
	v_mul_f32_e32 v181, v19, v181
	v_mul_f32_e32 v178, v16, v178
	v_mul_f32_e32 v179, v17, v179
	v_fma_f32 v34, v6, v38, v34
	v_fma_f32 v35, v7, v39, v35
	v_fma_f32 v32, v4, v36, v32
	v_fma_f32 v33, v5, v37, v33
	s_waitcnt lgkmcnt(6)
	v_fma_f32 v36, v22, v184, v180
	v_fma_f32 v37, v23, v185, v181
	v_fma_f32 v38, v20, v182, v178
	v_fma_f32 v39, v21, v183, v179
	v_fma_f32 v32, v8, v40, v32
	v_fma_f32 v33, v9, v41, v33
	v_fma_f32 v34, v10, v42, v34
	v_fma_f32 v35, v11, v43, v35
	s_waitcnt lgkmcnt(3)
	v_fma_f32 v38, v24, v194, v38
	v_fma_f32 v39, v25, v195, v39
	v_fma_f32 v36, v26, v196, v36
	v_fma_f32 v37, v27, v197, v37
	v_fma_f32 v34, v14, v46, v34
	v_fma_f32 v35, v15, v47, v35
	v_fma_f32 v32, v12, v44, v32
	v_fma_f32 v33, v13, v45, v33
	s_waitcnt lgkmcnt(2)
	v_fma_f32 v36, v30, v200, v36
	v_fma_f32 v37, v31, v201, v37
	v_fma_f32 v38, v28, v198, v38
	v_fma_f32 v39, v29, v199, v39
	v_add_f32_e32 v32, v32, v33
	v_add_f32_e32 v33, v34, v35
	v_add_u32_e32 v159, 0x4000, v61
	v_add_f32_e32 v32, v32, v33
	v_add_f32_e32 v33, v38, v39
	v_add_f32_e32 v34, v36, v37
	ds_read2_b32 v[210:211], v159 offset0:128 offset1:160
	ds_read_b32 v159, v158 offset:17664
	ds_read_b64 v[194:195], v50 offset:20840
	v_add_f32_e32 v33, v33, v34
	v_add_f32_e32 v32, v32, v33
	v_mov_b32_e32 v33, v32
	s_nop 1
	v_permlane32_swap_b32_e32 v32, v33
	v_add_f32_e32 v161, v32, v33
	s_waitcnt lgkmcnt(0)
	v_cndmask_b32_e64 v178, v159, v161, s[6:7]
	v_mul_f32_e32 v164, v2, v164
	v_mul_f32_e32 v165, v3, v165
	v_mul_f32_e32 v162, v0, v162
	v_mul_f32_e32 v163, v1, v163
	v_mfma_f32_32x32x2_f32 v[32:47], v211, v178, v[16:31]
	v_fma_f32 v18, v18, v188, 0
	v_fma_f32 v19, v19, v189, 0
	v_fma_f32 v16, v16, v186, 0
	v_fma_f32 v17, v17, v187, 0
	v_fma_f32 v164, v6, v168, v164
	v_fma_f32 v165, v7, v169, v165
	v_fma_f32 v162, v4, v166, v162
	v_fma_f32 v163, v5, v167, v163
	v_fma_f32 v18, v22, v192, v18
	v_fma_f32 v19, v23, v193, v19
	v_fma_f32 v16, v20, v190, v16
	v_fma_f32 v17, v21, v191, v17
	v_fma_f32 v20, v8, v170, v162
	v_fma_f32 v21, v9, v171, v163
	v_fma_f32 v22, v10, v172, v164
	v_fma_f32 v23, v11, v173, v165
	v_fma_f32 v20, v12, v174, v20
	v_fma_f32 v21, v13, v175, v21
	v_fma_f32 v22, v14, v176, v22
	v_fma_f32 v23, v15, v177, v23
	v_fma_f32 v16, v24, v202, v16
	v_fma_f32 v17, v25, v203, v17
	v_fma_f32 v18, v26, v204, v18
	v_fma_f32 v19, v27, v205, v19
	v_fma_f32 v16, v28, v206, v16
	v_fma_f32 v17, v29, v207, v17
	v_fma_f32 v18, v30, v208, v18
	v_fma_f32 v19, v31, v209, v19
	v_add_f32_e32 v20, v20, v21
	v_mfma_f32_32x32x2_f32 v[0:15], v210, v178, v[0:15]
	v_add_f32_e32 v21, v22, v23
	v_add_f32_e32 v16, v16, v17
	v_add_f32_e32 v17, v18, v19
	v_add_f32_e32 v20, v20, v21
	v_add_f32_e32 v16, v16, v17
	v_add_f32_e32 v16, v20, v16
	v_mov_b32_e32 v18, v16
	s_nop 1
	v_permlane32_swap_b32_e32 v16, v18
	s_and_saveexec_b64 s[28:29], s[6:7]
	s_cbranch_execz .LBB0_529
	s_add_i32 s39, s26, 13
	s_add_i32 s41, s30, 26
	s_and_b64 s[34:35], s[8:9], exec
	s_cselect_b32 s34, s39, s41
	s_waitcnt lgkmcnt(0)
	v_mul_f32_e32 v19, v161, v194
	v_mul_f32_e32 v17, v159, v195
	v_pk_add_f32 v[16:17], v[16:17], v[18:19]
	s_ashr_i32 s35, s34, 31
	v_add_f32_e32 v18, v16, v17
	v_lshl_add_u64 v[16:17], v[66:67], 0, s[34:35]
	v_lshlrev_b64 v[16:17], 11, v[16:17]
	v_lshl_add_u64 v[16:17], v[68:69], 0, v[16:17]
	global_store_dword v[16:17], v18, off
.LBB0_529:
	s_or_b64 exec, exec, s[28:29]
	ds_read_b128 v[18:21], v59 offset:17920
	ds_read_b128 v[22:25], v59 offset:17952
	ds_read_b128 v[26:29], v59 offset:18688
	ds_read_b128 v[162:165], v59 offset:18720
	ds_read_b128 v[166:169], v59 offset:17984
	ds_read_b128 v[170:173], v59 offset:18016
	ds_read_b128 v[174:177], v59 offset:18752
	ds_read_b128 v[178:181], v59 offset:18784
	ds_read_b128 v[182:185], v59 offset:18048
	ds_read_b128 v[186:189], v59 offset:18080
	ds_read_b128 v[190:193], v59 offset:18112
	ds_read_b128 v[194:197], v59 offset:18144
	s_waitcnt lgkmcnt(11)
	v_mul_f32_e32 v20, v2, v20
	v_mul_f32_e32 v21, v3, v21
	v_mul_f32_e32 v18, v0, v18
	v_mul_f32_e32 v19, v1, v19
	s_waitcnt lgkmcnt(3)
	v_mul_f32_e32 v30, v34, v184
	v_mul_f32_e32 v31, v35, v185
	v_mul_f32_e32 v182, v32, v182
	v_mul_f32_e32 v183, v33, v183
	v_fma_f32 v20, v6, v24, v20
	v_fma_f32 v21, v7, v25, v21
	v_fma_f32 v18, v4, v22, v18
	v_fma_f32 v19, v5, v23, v19
	s_waitcnt lgkmcnt(2)
	v_fma_f32 v22, v38, v188, v30
	v_fma_f32 v23, v39, v189, v31
	v_fma_f32 v24, v36, v186, v182
	v_fma_f32 v25, v37, v187, v183
	v_fma_f32 v18, v8, v166, v18
	v_fma_f32 v19, v9, v167, v19
	v_fma_f32 v20, v10, v168, v20
	v_fma_f32 v21, v11, v169, v21
	s_waitcnt lgkmcnt(1)
	v_fma_f32 v22, v42, v192, v22
	v_fma_f32 v23, v43, v193, v23
	v_add_u32_e32 v16, 0x4400, v61
	v_fma_f32 v24, v40, v190, v24
	v_fma_f32 v25, v41, v191, v25
	v_fma_f32 v20, v14, v172, v20
	v_fma_f32 v21, v15, v173, v21
	v_fma_f32 v18, v12, v170, v18
	v_fma_f32 v19, v13, v171, v19
	s_waitcnt lgkmcnt(0)
	v_fma_f32 v22, v46, v196, v22
	v_fma_f32 v23, v47, v197, v23
	ds_read2_b32 v[198:199], v16 offset0:192 offset1:224
	ds_read_b32 v17, v158 offset:18944
	ds_read_b64 v[170:171], v50 offset:20848
	v_fma_f32 v24, v44, v194, v24
	v_fma_f32 v25, v45, v195, v25
	v_add_f32_e32 v16, v18, v19
	v_add_f32_e32 v18, v20, v21
	v_add_f32_e32 v19, v22, v23
	v_mul_f32_e32 v20, v2, v28
	v_mul_f32_e32 v21, v3, v29
	v_mul_f32_e32 v22, v0, v26
	v_mul_f32_e32 v23, v1, v27
	v_add_f32_e32 v16, v16, v18
	v_add_f32_e32 v18, v24, v25
	v_fma_f32 v20, v6, v164, v20
	v_fma_f32 v21, v7, v165, v21
	v_fma_f32 v22, v4, v162, v22
	v_fma_f32 v23, v5, v163, v23
	v_add_f32_e32 v18, v18, v19
	v_fma_f32 v22, v8, v174, v22
	v_fma_f32 v23, v9, v175, v23
	v_fma_f32 v20, v10, v176, v20
	v_fma_f32 v21, v11, v177, v21
	v_add_f32_e32 v16, v16, v18
	v_fma_f32 v166, v14, v180, v20
	v_fma_f32 v167, v15, v181, v21
	v_fma_f32 v168, v12, v178, v22
	v_fma_f32 v169, v13, v179, v23
	ds_read_b128 v[20:23], v59 offset:18816
	ds_read_b128 v[24:27], v59 offset:18848
	ds_read_b128 v[28:31], v59 offset:18880
	ds_read_b128 v[162:165], v59 offset:18912
	v_mov_b32_e32 v18, v16
	s_nop 1
	v_permlane32_swap_b32_e32 v16, v18
	s_waitcnt lgkmcnt(3)
	v_mul_f32_e32 v22, v34, v22
	v_mul_f32_e32 v23, v35, v23
	v_mul_f32_e32 v20, v32, v20
	v_mul_f32_e32 v21, v33, v21
	v_add_f32_e32 v19, v16, v18
	s_waitcnt lgkmcnt(2)
	v_fma_f32 v22, v38, v26, v22
	v_fma_f32 v23, v39, v27, v23
	v_fma_f32 v20, v36, v24, v20
	v_fma_f32 v21, v37, v25, v21
	v_cndmask_b32_e64 v16, v17, v19, s[6:7]
	s_waitcnt lgkmcnt(1)
	v_fma_f32 v20, v40, v28, v20
	v_fma_f32 v21, v41, v29, v21
	v_fma_f32 v22, v42, v30, v22
	v_fma_f32 v23, v43, v31, v23
	v_mfma_f32_32x32x2_f32 v[0:15], v198, v16, v[0:15]
	s_waitcnt lgkmcnt(0)
	v_fma_f32 v22, v46, v164, v22
	v_fma_f32 v23, v47, v165, v23
	v_fma_f32 v20, v44, v162, v20
	v_fma_f32 v21, v45, v163, v21
	v_add_f32_e32 v18, v166, v167
	v_mfma_f32_32x32x2_f32 v[32:47], v199, v16, v[32:47]
	v_add_f32_e32 v16, v168, v169
	v_add_f32_e32 v16, v16, v18
	v_add_f32_e32 v18, v20, v21
	v_add_f32_e32 v20, v22, v23
	v_add_f32_e32 v18, v18, v20
	v_add_f32_e32 v16, v16, v18
	v_mov_b32_e32 v18, v16
	s_nop 1
	v_permlane32_swap_b32_e32 v16, v18
	s_and_saveexec_b64 s[28:29], s[6:7]
	s_cbranch_execz .LBB0_531
	s_add_i32 s39, s26, 14
	s_add_i32 s41, s30, 25
	s_and_b64 s[34:35], s[8:9], exec
	s_cselect_b32 s34, s39, s41
	s_waitcnt lgkmcnt(0)
	v_mul_f32_e32 v19, v19, v170
	v_mul_f32_e32 v17, v17, v171
	v_pk_add_f32 v[16:17], v[16:17], v[18:19]
	s_ashr_i32 s35, s34, 31
	v_add_f32_e32 v18, v16, v17
	v_lshl_add_u64 v[16:17], v[66:67], 0, s[34:35]
	v_lshlrev_b64 v[16:17], 11, v[16:17]
	v_lshl_add_u64 v[16:17], v[68:69], 0, v[16:17]
	global_store_dword v[16:17], v18, off
.LBB0_531:
	s_or_b64 exec, exec, s[28:29]
	ds_read_b128 v[16:19], v59 offset:19200
	ds_read_b128 v[20:23], v59 offset:19232
	ds_read_b128 v[162:165], v59 offset:19968
	ds_read_b128 v[166:169], v59 offset:20000
	ds_read_b128 v[24:27], v59 offset:19264
	ds_read_b128 v[28:31], v59 offset:19296
	ds_read_b128 v[170:173], v59 offset:20032
	ds_read_b128 v[174:177], v59 offset:20064
	ds_read_b128 v[178:181], v59 offset:19328
	ds_read_b128 v[182:185], v59 offset:19360
	ds_read_b128 v[186:189], v59 offset:20096
	ds_read_b128 v[190:193], v59 offset:20128
	ds_read_b128 v[194:197], v59 offset:19392
	ds_read_b128 v[198:201], v59 offset:19424
	ds_read_b128 v[202:205], v59 offset:20160
	ds_read_b128 v[206:209], v59 offset:20192
	v_add_u32_e32 v59, 0x4c00, v61
	s_waitcnt lgkmcnt(14)
	v_mul_f32_e32 v18, v2, v18
	v_mul_f32_e32 v19, v3, v19
	v_mul_f32_e32 v16, v0, v16
	v_mul_f32_e32 v17, v1, v17
	ds_read2_b32 v[210:211], v59 offset1:32
	ds_read_b32 v59, v158 offset:20224
	s_waitcnt lgkmcnt(9)
	v_mul_f32_e32 v158, v34, v180
	v_mul_f32_e32 v159, v35, v181
	v_mul_f32_e32 v178, v32, v178
	v_mul_f32_e32 v179, v33, v179
	v_fma_f32 v18, v6, v22, v18
	v_fma_f32 v19, v7, v23, v19
	v_fma_f32 v16, v4, v20, v16
	v_fma_f32 v17, v5, v21, v17
	s_waitcnt lgkmcnt(8)
	v_fma_f32 v20, v38, v184, v158
	v_fma_f32 v21, v39, v185, v159
	v_fma_f32 v22, v36, v182, v178
	v_fma_f32 v23, v37, v183, v179
	v_fma_f32 v16, v8, v24, v16
	v_fma_f32 v17, v9, v25, v17
	v_fma_f32 v18, v10, v26, v18
	v_fma_f32 v19, v11, v27, v19
	s_waitcnt lgkmcnt(5)
	v_fma_f32 v22, v40, v194, v22
	v_fma_f32 v23, v41, v195, v23
	v_fma_f32 v20, v42, v196, v20
	v_fma_f32 v21, v43, v197, v21
	v_fma_f32 v18, v14, v30, v18
	v_fma_f32 v19, v15, v31, v19
	v_fma_f32 v16, v12, v28, v16
	v_fma_f32 v17, v13, v29, v17
	s_waitcnt lgkmcnt(4)
	v_fma_f32 v20, v46, v200, v20
	v_fma_f32 v21, v47, v201, v21
	v_fma_f32 v22, v44, v198, v22
	v_fma_f32 v23, v45, v199, v23
	v_add_f32_e32 v16, v16, v17
	v_add_f32_e32 v17, v18, v19
	v_add_f32_e32 v16, v16, v17
	v_add_f32_e32 v17, v22, v23
	v_add_f32_e32 v18, v20, v21
	v_add_f32_e32 v17, v17, v18
	v_add_f32_e32 v16, v16, v17
	v_mov_b32_e32 v17, v16
	s_nop 1
	v_permlane32_swap_b32_e32 v16, v17
	v_add_f32_e32 v61, v16, v17
	s_waitcnt lgkmcnt(0)
	v_cndmask_b32_e64 v161, v59, v61, s[6:7]
	v_mul_f32_e32 v158, v2, v164
	v_mul_f32_e32 v159, v3, v165
	v_mul_f32_e32 v162, v0, v162
	v_mul_f32_e32 v163, v1, v163
	v_mfma_f32_32x32x2_f32 v[16:31], v211, v161, v[32:47]
	v_fma_f32 v34, v34, v188, 0
	v_fma_f32 v35, v35, v189, 0
	v_fma_f32 v32, v32, v186, 0
	v_fma_f32 v33, v33, v187, 0
	v_fma_f32 v158, v6, v168, v158
	v_fma_f32 v159, v7, v169, v159
	v_fma_f32 v162, v4, v166, v162
	v_fma_f32 v163, v5, v167, v163
	v_fma_f32 v34, v38, v192, v34
	v_fma_f32 v35, v39, v193, v35
	v_fma_f32 v32, v36, v190, v32
	v_fma_f32 v33, v37, v191, v33
	v_fma_f32 v36, v8, v170, v162
	v_fma_f32 v37, v9, v171, v163
	v_fma_f32 v38, v10, v172, v158
	v_fma_f32 v39, v11, v173, v159
	v_fma_f32 v36, v12, v174, v36
	v_fma_f32 v37, v13, v175, v37
	v_fma_f32 v38, v14, v176, v38
	v_fma_f32 v39, v15, v177, v39
	v_fma_f32 v32, v40, v202, v32
	v_fma_f32 v33, v41, v203, v33
	v_fma_f32 v34, v42, v204, v34
	v_fma_f32 v35, v43, v205, v35
	v_fma_f32 v32, v44, v206, v32
	v_fma_f32 v33, v45, v207, v33
	v_fma_f32 v34, v46, v208, v34
	v_fma_f32 v35, v47, v209, v35
	v_add_f32_e32 v36, v36, v37
	v_mfma_f32_32x32x2_f32 v[0:15], v210, v161, v[0:15]
	v_add_f32_e32 v37, v38, v39
	v_add_f32_e32 v32, v32, v33
	v_add_f32_e32 v33, v34, v35
	v_add_f32_e32 v36, v36, v37
	v_add_f32_e32 v32, v32, v33
	v_add_f32_e32 v32, v36, v32
	v_mov_b32_e32 v34, v32
	s_nop 1
	v_permlane32_swap_b32_e32 v32, v34
	s_and_saveexec_b64 s[28:29], s[6:7]
	s_cbranch_execz .LBB0_533
	ds_read_b64 v[36:37], v50 offset:20856
	s_add_i32 s39, s26, 15
	s_add_i32 s41, s30, 24
	s_and_b64 s[34:35], s[8:9], exec
	s_cselect_b32 s34, s39, s41
	s_waitcnt lgkmcnt(0)
	v_mul_f32_e32 v35, v61, v36
	v_mul_f32_e32 v33, v59, v37
	v_pk_add_f32 v[32:33], v[32:33], v[34:35]
	s_ashr_i32 s35, s34, 31
	v_add_f32_e32 v34, v32, v33
	v_lshl_add_u64 v[32:33], v[66:67], 0, s[34:35]
	v_lshlrev_b64 v[32:33], 11, v[32:33]
	v_lshl_add_u64 v[32:33], v[68:69], 0, v[32:33]
	global_store_dword v[32:33], v34, off
